# v78 + 8 row-phase wave reductions (6-step ds_bpermute xor butterfly) replaced by DPP quad_perm/row_half_mirror/row_mirror + v_permlane16/32_swap adds (bit-identical order); fewer leftover s_nop
# speedup vs baseline: 1.0099x; 1.0010x over previous
.LBB0_114:
	s_add_i32 s24, s20, 0xffffe001
	s_cmpk_lt_i32 s14, 0x2000
	s_cselect_b32 s25, s15, 0
	s_cselect_b32 s24, s14, s24
	s_cselect_b32 s26, s1, s3
	s_cselect_b32 s27, s0, s2
	s_lshl_b64 s[24:25], s[24:25], 13
	s_add_u32 s24, s27, s24
	s_addc_u32 s25, s26, s25
	v_lshl_add_u64 v[40:41], s[24:25], 0, v[64:65]
	v_add_co_u32_e32 v100, vcc, s19, v40
	global_load_dwordx4 v[52:55], v64, s[24:25]
	global_load_dwordx4 v[44:47], v64, s[24:25] offset:1024
	global_load_dwordx4 v[36:39], v64, s[24:25] offset:2048
	global_load_dwordx4 v[32:35], v64, s[24:25] offset:3072
	v_addc_co_u32_e32 v101, vcc, 0, v41, vcc
	global_load_dwordx4 v[60:63], v[100:101], off
	global_load_dwordx4 v[56:59], v[100:101], off offset:1024
	global_load_dwordx4 v[48:51], v[100:101], off offset:2048
	global_load_dwordx4 v[40:43], v[100:101], off offset:3072
	s_waitcnt vmcnt(7)
	v_mov_b32_e32 v104, v53
	s_waitcnt vmcnt(6)
	v_mov_b32_e32 v105, v45
	v_mov_b32_e32 v108, v55
	v_mov_b32_e32 v109, v47
	v_mov_b32_e32 v100, v52
	v_mov_b32_e32 v101, v44
	v_mov_b32_e32 v102, v54
	v_mov_b32_e32 v103, v46
	s_waitcnt vmcnt(5)
	v_pk_mul_f32 v[110:111], v[38:39], v[38:39]
	v_pk_mul_f32 v[106:107], v[36:37], v[36:37]
	v_pk_mul_f32 v[104:105], v[104:105], v[104:105]
	v_pk_mul_f32 v[108:109], v[108:109], v[108:109]
	v_pk_mov_b32 v[130:131], v[106:107], v[110:111] op_sel:[1,0]
	v_mov_b32_e32 v107, v111
	v_pk_fma_f32 v[100:101], v[100:101], v[100:101], v[104:105]
	v_pk_fma_f32 v[102:103], v[102:103], v[102:103], v[108:109]
	s_waitcnt vmcnt(4)
	v_mul_f32_e32 v112, v33, v33
	v_mul_f32_e32 v114, v35, v35
	v_pk_add_f32 v[104:105], v[130:131], v[106:107]
	v_pk_add_f32 v[100:101], v[100:101], v[102:103]
	s_waitcnt vmcnt(3)
	v_mul_f32_e32 v128, v60, v60
	v_mul_f32_e32 v129, v61, v61
	v_mul_f32_e32 v138, v62, v62
	v_mul_f32_e32 v139, v63, v63
	v_pk_fma_f32 v[110:111], v[32:33], v[32:33], v[112:113] op_sel_hi:[1,1,0]
	v_pk_fma_f32 v[132:133], v[34:35], v[34:35], v[114:115] op_sel_hi:[1,1,0]
	v_pk_add_f32 v[102:103], v[104:105], v[104:105] op_sel:[0,1] op_sel_hi:[1,0]
	v_pk_add_f32 v[100:101], v[100:101], v[100:101] op_sel:[0,1] op_sel_hi:[1,0]
	s_waitcnt vmcnt(2)
	v_pk_mul_f32 v[118:119], v[58:59], v[58:59]
	v_pk_mul_f32 v[116:117], v[56:57], v[56:57]
	v_mov_b32_e32 v111, v138
	v_mov_b32_e32 v133, v139
	v_mov_b32_e32 v103, v129
	v_mov_b32_e32 v101, v128
	v_pk_mov_b32 v[134:135], v[116:117], v[118:119] op_sel:[1,0]
	v_mov_b32_e32 v117, v119
	v_pk_add_f32 v[104:105], v[110:111], v[132:133]
	v_pk_add_f32 v[100:101], v[100:101], v[102:103]
	s_waitcnt vmcnt(1)
	v_mul_f32_e32 v120, v49, v49
	v_mul_f32_e32 v122, v51, v51
	v_pk_add_f32 v[106:107], v[134:135], v[116:117]
	v_pk_add_f32 v[100:101], v[100:101], v[104:105]
	s_waitcnt vmcnt(0)
	v_mul_f32_e32 v140, v40, v40
	v_mul_f32_e32 v141, v41, v41
	v_mul_f32_e32 v142, v42, v42
	v_mul_f32_e32 v143, v43, v43
	v_pk_fma_f32 v[118:119], v[48:49], v[48:49], v[120:121] op_sel_hi:[1,1,0]
	v_pk_fma_f32 v[136:137], v[50:51], v[50:51], v[122:123] op_sel_hi:[1,1,0]
	v_pk_add_f32 v[106:107], v[106:107], v[106:107] op_sel:[0,1] op_sel_hi:[1,0]
	v_pk_add_f32 v[100:101], v[100:101], v[100:101] op_sel:[0,1] op_sel_hi:[1,0]
	v_mov_b32_e32 v119, v142
	v_mov_b32_e32 v137, v143
	v_mov_b32_e32 v107, v141
	v_mov_b32_e32 v101, v140
	v_pk_add_f32 v[108:109], v[118:119], v[136:137]
	v_pk_add_f32 v[100:101], v[100:101], v[106:107]
	s_add_i32 s20, s20, 1
	v_pk_add_f32 v[100:101], v[100:101], v[108:109]
	s_add_u32 s14, s14, 1
	v_add_f32_e32 v100, v100, v101
	s_addc_u32 s15, s15, 0
	s_cmp_ge_i32 s20, s18
	s_waitcnt lgkmcnt(0)
	s_waitcnt lgkmcnt(0)
	s_waitcnt lgkmcnt(0)
	s_waitcnt lgkmcnt(0)
	s_waitcnt lgkmcnt(0)
	s_waitcnt lgkmcnt(0)
	s_nop 1
	v_add_f32_dpp v100, v100, v100 quad_perm:[1,0,3,2] row_mask:0xf bank_mask:0xf
	s_nop 1
	v_add_f32_dpp v100, v100, v100 quad_perm:[2,3,0,1] row_mask:0xf bank_mask:0xf
	s_nop 1
	v_add_f32_dpp v100, v100, v100 row_half_mirror row_mask:0xf bank_mask:0xf
	s_nop 1
	v_add_f32_dpp v100, v100, v100 row_mirror row_mask:0xf bank_mask:0xf
	v_mov_b32_e32 v101, v100
	s_nop 1
	v_permlane16_swap_b32_e32 v100, v101
	v_add_f32_e32 v100, v100, v101
	v_mov_b32_e32 v101, v100
	s_nop 1
	v_permlane32_swap_b32_e32 v100, v101
	v_add_f32_e32 v100, v100, v101
	v_fmamk_f32 v100, v100, 0x3a000000, v127
	v_mul_f32_e32 v101, 0x4b800000, v100
	v_cmp_gt_f32_e32 vcc, s21, v100
	s_nop 1
	v_cndmask_b32_e32 v100, v100, v101, vcc
	v_rsq_f32_e32 v100, v100
	s_nop 0
	v_mul_f32_e32 v101, 0x45800000, v100
	v_cndmask_b32_e32 v100, v100, v101, vcc
	v_pk_mul_f32 v[52:53], v[52:53], v[100:101] op_sel_hi:[1,0]
	v_pk_mul_f32 v[54:55], v[54:55], v[100:101] op_sel_hi:[1,0]
	v_pk_mul_f32 v[44:45], v[44:45], v[100:101] op_sel_hi:[1,0]
	v_pk_mul_f32 v[46:47], v[46:47], v[100:101] op_sel_hi:[1,0]
	v_pk_mul_f32 v[36:37], v[36:37], v[100:101] op_sel_hi:[1,0]
	v_pk_mul_f32 v[38:39], v[38:39], v[100:101] op_sel_hi:[1,0]
	v_pk_mul_f32 v[32:33], v[32:33], v[100:101] op_sel_hi:[1,0]
	v_pk_mul_f32 v[34:35], v[34:35], v[100:101] op_sel_hi:[1,0]
	v_pk_mul_f32 v[60:61], v[60:61], v[100:101] op_sel_hi:[1,0]
	v_pk_mul_f32 v[62:63], v[62:63], v[100:101] op_sel_hi:[1,0]
	v_pk_mul_f32 v[56:57], v[56:57], v[100:101] op_sel_hi:[1,0]
	v_pk_mul_f32 v[58:59], v[58:59], v[100:101] op_sel_hi:[1,0]
	v_pk_mul_f32 v[48:49], v[48:49], v[100:101] op_sel_hi:[1,0]
	v_pk_mul_f32 v[50:51], v[50:51], v[100:101] op_sel_hi:[1,0]
	v_pk_mul_f32 v[40:41], v[40:41], v[100:101] op_sel_hi:[1,0]
	v_pk_mul_f32 v[42:43], v[42:43], v[100:101] op_sel_hi:[1,0]
	v_pk_fma_f32 v[54:55], v[66:67], v[54:55], v[2:3]
	v_pk_fma_f32 v[52:53], v[68:69], v[52:53], v[0:1]
	v_pk_fma_f32 v[46:47], v[70:71], v[46:47], v[6:7]
	v_pk_fma_f32 v[44:45], v[72:73], v[44:45], v[4:5]
	v_pk_fma_f32 v[38:39], v[74:75], v[38:39], v[10:11]
	v_pk_fma_f32 v[36:37], v[76:77], v[36:37], v[8:9]
	v_pk_fma_f32 v[34:35], v[78:79], v[34:35], v[14:15]
	v_pk_fma_f32 v[32:33], v[80:81], v[32:33], v[12:13]
	v_pk_fma_f32 v[62:63], v[82:83], v[62:63], v[18:19]
	v_pk_fma_f32 v[60:61], v[84:85], v[60:61], v[16:17]
	v_pk_fma_f32 v[58:59], v[86:87], v[58:59], v[22:23]
	v_pk_fma_f32 v[56:57], v[88:89], v[56:57], v[20:21]
	v_pk_fma_f32 v[50:51], v[90:91], v[50:51], v[26:27]
	v_pk_fma_f32 v[48:49], v[92:93], v[48:49], v[24:25]
	v_pk_fma_f32 v[42:43], v[94:95], v[42:43], v[30:31]
	v_pk_fma_f32 v[40:41], v[96:97], v[40:41], v[28:29]
	v_bfe_u32 v100, v52, 16, 1
	v_bfe_u32 v102, v54, 16, 1
	v_bfe_u32 v101, v53, 16, 1
	v_bfe_u32 v103, v55, 16, 1
	v_bfe_u32 v104, v44, 16, 1
	v_bfe_u32 v106, v46, 16, 1
	v_bfe_u32 v108, v36, 16, 1
	v_bfe_u32 v110, v38, 16, 1
	v_bfe_u32 v112, v32, 16, 1
	v_bfe_u32 v114, v33, 16, 1
	v_bfe_u32 v116, v34, 16, 1
	v_bfe_u32 v117, v35, 16, 1
	v_bfe_u32 v118, v60, 16, 1
	v_bfe_u32 v119, v61, 16, 1
	v_bfe_u32 v120, v62, 16, 1
	v_bfe_u32 v122, v63, 16, 1
	v_bfe_u32 v128, v56, 16, 1
	v_bfe_u32 v130, v58, 16, 1
	v_bfe_u32 v132, v48, 16, 1
	v_bfe_u32 v134, v50, 16, 1
	v_bfe_u32 v136, v40, 16, 1
	v_bfe_u32 v137, v41, 16, 1
	v_bfe_u32 v138, v42, 16, 1
	v_bfe_u32 v139, v43, 16, 1
	v_add3_u32 v52, v52, v100, s22
	v_add3_u32 v54, v54, v102, s22
	v_bfe_u32 v105, v45, 16, 1
	v_bfe_u32 v107, v47, 16, 1
	v_bfe_u32 v109, v37, 16, 1
	v_bfe_u32 v111, v39, 16, 1
	v_bfe_u32 v129, v57, 16, 1
	v_bfe_u32 v131, v59, 16, 1
	v_bfe_u32 v133, v49, 16, 1
	v_bfe_u32 v135, v51, 16, 1
	v_add3_u32 v53, v53, v101, s22
	v_add3_u32 v55, v55, v103, s22
	v_add3_u32 v44, v44, v104, s22
	v_add3_u32 v46, v46, v106, s22
	v_add3_u32 v36, v36, v108, s22
	v_add3_u32 v38, v38, v110, s22
	v_add3_u32 v32, v32, v112, s22
	v_add3_u32 v100, v33, v114, s22
	v_add3_u32 v33, v34, v116, s22
	v_add3_u32 v101, v35, v117, s22
	v_add3_u32 v34, v60, v118, s22
	v_add3_u32 v60, v61, v119, s22
	v_add3_u32 v35, v62, v120, s22
	v_add3_u32 v61, v63, v122, s22
	v_add3_u32 v56, v56, v128, s22
	v_add3_u32 v58, v58, v130, s22
	v_add3_u32 v48, v48, v132, s22
	v_add3_u32 v50, v50, v134, s22
	v_add3_u32 v40, v40, v136, s22
	v_add3_u32 v62, v41, v137, s22
	v_add3_u32 v41, v42, v138, s22
	v_add3_u32 v63, v43, v139, s22
	v_lshrrev_b32_e32 v42, 16, v52
	v_lshrrev_b32_e32 v43, 16, v54
	v_add3_u32 v45, v45, v105, s22
	v_add3_u32 v47, v47, v107, s22
	v_add3_u32 v37, v37, v109, s22
	v_add3_u32 v39, v39, v111, s22
	v_add3_u32 v57, v57, v129, s22
	v_add3_u32 v59, v59, v131, s22
	v_add3_u32 v49, v49, v133, s22
	v_add3_u32 v51, v51, v135, s22
	v_lshrrev_b32_e32 v44, 16, v44
	v_lshrrev_b32_e32 v46, 16, v46
	v_lshrrev_b32_e32 v36, 16, v36
	v_lshrrev_b32_e32 v38, 16, v38
	v_lshrrev_b32_e32 v52, 16, v32
	v_lshrrev_b32_e32 v54, 16, v33
	v_lshrrev_b32_e32 v102, 16, v34
	v_lshrrev_b32_e32 v103, 16, v35
	v_lshrrev_b32_e32 v56, 16, v56
	v_lshrrev_b32_e32 v58, 16, v58
	v_lshrrev_b32_e32 v48, 16, v48
	v_lshrrev_b32_e32 v50, 16, v50
	v_lshrrev_b32_e32 v104, 16, v40
	v_lshrrev_b32_e32 v105, 16, v41
	v_and_or_b32 v32, v53, s23, v42
	v_and_or_b32 v33, v55, s23, v43
	v_and_or_b32 v34, v45, s23, v44
	v_and_or_b32 v35, v47, s23, v46
	v_and_or_b32 v36, v37, s23, v36
	v_and_or_b32 v37, v39, s23, v38
	v_and_or_b32 v38, v100, s23, v52
	v_and_or_b32 v39, v101, s23, v54
	v_and_or_b32 v40, v60, s23, v102
	v_and_or_b32 v41, v61, s23, v103
	v_and_or_b32 v42, v57, s23, v56
	v_and_or_b32 v43, v59, s23, v58
	v_and_or_b32 v44, v49, s23, v48
	v_and_or_b32 v45, v51, s23, v50
	v_and_or_b32 v46, v62, s23, v104
	v_and_or_b32 v47, v63, s23, v105
	global_store_dwordx2 v[98:99], v[32:33], off offset:-3584
	global_store_dwordx2 v[98:99], v[34:35], off offset:-3072
	global_store_dwordx2 v[98:99], v[36:37], off offset:-2560
	global_store_dwordx2 v[98:99], v[38:39], off offset:-2048
	global_store_dwordx2 v[98:99], v[40:41], off offset:-1536
	global_store_dwordx2 v[98:99], v[42:43], off offset:-1024
	global_store_dwordx2 v[98:99], v[44:45], off offset:-512
	global_store_dwordx2 v[98:99], v[46:47], off
	v_lshl_add_u64 v[98:99], v[98:99], 0, s[16:17]
	s_cbranch_scc0 .LBB0_114
	s_branch .LBB0_120

.LBB0_119:
	s_add_i32 s12, s14, 0xffffe000
	s_ashr_i32 s13, s12, 12
	s_add_i32 s13, s13, 1
	s_cmpk_lt_i32 s14, 0x2000
	s_cselect_b32 s16, 0, s13
	s_cselect_b32 s13, s15, 0
	s_cselect_b32 s12, s14, s12
	s_cselect_b32 s17, s1, s3
	s_cselect_b32 s18, s0, s2
	s_lshl_b64 s[12:13], s[12:13], 13
	s_add_u32 s12, s18, s12
	s_addc_u32 s13, s17, s13
	v_lshl_add_u64 v[0:1], s[12:13], 0, v[124:125]
	v_add_co_u32_e32 v0, vcc, s8, v0
	global_load_dwordx4 v[36:39], v124, s[12:13]
	global_load_dwordx4 v[28:31], v124, s[12:13] offset:1024
	global_load_dwordx4 v[20:23], v124, s[12:13] offset:2048
	global_load_dwordx4 v[16:19], v124, s[12:13] offset:3072
	v_addc_co_u32_e32 v1, vcc, 0, v1, vcc
	global_load_dwordx4 v[44:47], v[0:1], off
	global_load_dwordx4 v[40:43], v[0:1], off offset:1024
	global_load_dwordx4 v[32:35], v[0:1], off offset:2048
	global_load_dwordx4 v[24:27], v[0:1], off offset:3072
	v_mad_i64_i32 v[64:65], s[12:13], s16, v173, v[136:137]
	v_add_co_u32_e32 v72, vcc, s8, v64
	v_mad_i64_i32 v[66:67], s[12:13], s16, v173, v[138:139]
	s_nop 0
	v_addc_co_u32_e32 v73, vcc, 0, v65, vcc
	v_add_co_u32_e32 v74, vcc, s8, v66
	global_load_dwordx4 v[48:51], v[126:127], off
	global_load_dwordx4 v[52:55], v[126:127], off offset:1024
	global_load_dwordx4 v[184:187], v[64:65], off
	global_load_dwordx4 v[120:123], v[64:65], off offset:1024
	global_load_dwordx4 v[4:7], v[66:67], off
	global_load_dwordx4 v[0:3], v[66:67], off offset:1024
	global_load_dwordx4 v[56:59], v[126:127], off offset:2048
	global_load_dwordx4 v[60:63], v[126:127], off offset:3072
	global_load_dwordx4 v[116:119], v[64:65], off offset:2048
	global_load_dwordx4 v[112:115], v[64:65], off offset:3072
	global_load_dwordx4 v[12:15], v[66:67], off offset:2048
	global_load_dwordx4 v[8:11], v[66:67], off offset:3072
	v_addc_co_u32_e32 v75, vcc, 0, v67, vcc
	global_load_dwordx4 v[80:83], v[128:129], off
	global_load_dwordx4 v[84:87], v[130:131], off
	global_load_dwordx4 v[108:111], v[72:73], off
	global_load_dwordx4 v[104:107], v[72:73], off offset:1024
	global_load_dwordx4 v[68:71], v[74:75], off
	global_load_dwordx4 v[64:67], v[74:75], off offset:1024
	global_load_dwordx4 v[88:91], v[132:133], off
	global_load_dwordx4 v[92:95], v[134:135], off
	global_load_dwordx4 v[100:103], v[72:73], off offset:2048
	global_load_dwordx4 v[96:99], v[72:73], off offset:3072
	global_load_dwordx4 v[76:79], v[74:75], off offset:2048
	s_nop 0
	global_load_dwordx4 v[72:75], v[74:75], off offset:3072
	s_waitcnt vmcnt(31)
	v_mov_b32_e32 v146, v37
	s_waitcnt vmcnt(30)
	v_mov_b32_e32 v147, v29
	v_mov_b32_e32 v148, v39
	v_mov_b32_e32 v149, v31
	v_mov_b32_e32 v142, v36
	v_mov_b32_e32 v143, v28
	v_mov_b32_e32 v144, v38
	v_mov_b32_e32 v145, v30
	s_waitcnt vmcnt(29)
	v_pk_mul_f32 v[152:153], v[22:23], v[22:23]
	v_pk_mul_f32 v[150:151], v[20:21], v[20:21]
	v_pk_mul_f32 v[146:147], v[146:147], v[146:147]
	v_pk_mul_f32 v[148:149], v[148:149], v[148:149]
	s_waitcnt vmcnt(21)
	v_pk_add_f32 v[164:165], v[184:185], 1.0 op_sel_hi:[1,0]
	v_pk_mov_b32 v[184:185], v[150:151], v[152:153] op_sel:[1,0]
	v_mov_b32_e32 v151, v153
	v_pk_fma_f32 v[142:143], v[142:143], v[142:143], v[146:147]
	v_pk_fma_f32 v[144:145], v[144:145], v[144:145], v[148:149]
	v_mul_f32_e32 v154, v17, v17
	v_mul_f32_e32 v156, v19, v19
	v_pk_add_f32 v[146:147], v[184:185], v[150:151]
	v_pk_add_f32 v[142:143], v[142:143], v[144:145]
	v_mul_f32_e32 v175, v44, v44
	v_mul_f32_e32 v177, v45, v45
	v_mul_f32_e32 v178, v46, v46
	v_mul_f32_e32 v179, v47, v47
	v_pk_add_f32 v[162:163], v[186:187], 1.0 op_sel_hi:[1,0]
	v_pk_fma_f32 v[152:153], v[16:17], v[16:17], v[154:155] op_sel_hi:[1,1,0]
	v_pk_fma_f32 v[186:187], v[18:19], v[18:19], v[156:157] op_sel_hi:[1,1,0]
	v_pk_add_f32 v[144:145], v[146:147], v[146:147] op_sel:[0,1] op_sel_hi:[1,0]
	v_pk_add_f32 v[142:143], v[142:143], v[142:143] op_sel:[0,1] op_sel_hi:[1,0]
	v_pk_mul_f32 v[160:161], v[42:43], v[42:43]
	v_pk_mul_f32 v[158:159], v[40:41], v[40:41]
	v_mov_b32_e32 v153, v178
	v_mov_b32_e32 v187, v179
	v_mov_b32_e32 v145, v177
	v_mov_b32_e32 v143, v175
	v_pk_mov_b32 v[188:189], v[158:159], v[160:161] op_sel:[1,0]
	v_mov_b32_e32 v159, v161
	v_pk_add_f32 v[146:147], v[152:153], v[186:187]
	v_pk_add_f32 v[142:143], v[142:143], v[144:145]
	v_mul_f32_e32 v166, v33, v33
	v_mul_f32_e32 v168, v35, v35
	v_pk_add_f32 v[148:149], v[188:189], v[158:159]
	v_pk_add_f32 v[142:143], v[142:143], v[146:147]
	v_mul_f32_e32 v180, v24, v24
	v_mul_f32_e32 v181, v25, v25
	v_mul_f32_e32 v182, v26, v26
	v_mul_f32_e32 v183, v27, v27
	v_pk_fma_f32 v[160:161], v[32:33], v[32:33], v[166:167] op_sel_hi:[1,1,0]
	v_pk_fma_f32 v[190:191], v[34:35], v[34:35], v[168:169] op_sel_hi:[1,1,0]
	v_pk_add_f32 v[148:149], v[148:149], v[148:149] op_sel:[0,1] op_sel_hi:[1,0]
	v_pk_add_f32 v[142:143], v[142:143], v[142:143] op_sel:[0,1] op_sel_hi:[1,0]
	v_mov_b32_e32 v161, v182
	v_mov_b32_e32 v191, v183
	v_mov_b32_e32 v149, v181
	v_mov_b32_e32 v143, v180
	v_pk_add_f32 v[150:151], v[160:161], v[190:191]
	v_pk_add_f32 v[142:143], v[142:143], v[148:149]
	s_waitcnt vmcnt(20)
	v_pk_add_f32 v[122:123], v[122:123], 1.0 op_sel_hi:[1,0]
	v_pk_add_f32 v[142:143], v[142:143], v[150:151]
	v_pk_add_f32 v[120:121], v[120:121], 1.0 op_sel_hi:[1,0]
	v_add_f32_e32 v142, v142, v143
	s_waitcnt vmcnt(15)
	v_pk_add_f32 v[118:119], v[118:119], 1.0 op_sel_hi:[1,0]
	v_pk_add_f32 v[116:117], v[116:117], 1.0 op_sel_hi:[1,0]
	s_waitcnt vmcnt(14)
	v_pk_add_f32 v[114:115], v[114:115], 1.0 op_sel_hi:[1,0]
	v_pk_add_f32 v[112:113], v[112:113], 1.0 op_sel_hi:[1,0]
	s_waitcnt lgkmcnt(0)
	s_waitcnt vmcnt(9)
	v_pk_add_f32 v[110:111], v[110:111], 1.0 op_sel_hi:[1,0]
	v_pk_add_f32 v[108:109], v[108:109], 1.0 op_sel_hi:[1,0]
	s_waitcnt vmcnt(8)
	v_pk_add_f32 v[106:107], v[106:107], 1.0 op_sel_hi:[1,0]
	v_pk_add_f32 v[104:105], v[104:105], 1.0 op_sel_hi:[1,0]
	s_waitcnt lgkmcnt(0)
	s_waitcnt vmcnt(3)
	v_pk_add_f32 v[102:103], v[102:103], 1.0 op_sel_hi:[1,0]
	v_pk_add_f32 v[100:101], v[100:101], 1.0 op_sel_hi:[1,0]
	s_waitcnt vmcnt(2)
	v_pk_add_f32 v[98:99], v[98:99], 1.0 op_sel_hi:[1,0]
	v_pk_add_f32 v[96:97], v[96:97], 1.0 op_sel_hi:[1,0]
	s_waitcnt lgkmcnt(0)
	s_add_u32 s14, s14, s50
	s_addc_u32 s15, s15, s51
	s_cmpk_gt_i32 s14, 0x3fff
	s_waitcnt lgkmcnt(0)
	s_waitcnt lgkmcnt(0)
	s_waitcnt lgkmcnt(0)
	s_nop 1
	v_add_f32_dpp v142, v142, v142 quad_perm:[1,0,3,2] row_mask:0xf bank_mask:0xf
	s_nop 1
	v_add_f32_dpp v142, v142, v142 quad_perm:[2,3,0,1] row_mask:0xf bank_mask:0xf
	s_nop 1
	v_add_f32_dpp v142, v142, v142 row_half_mirror row_mask:0xf bank_mask:0xf
	s_nop 1
	v_add_f32_dpp v142, v142, v142 row_mirror row_mask:0xf bank_mask:0xf
	v_mov_b32_e32 v143, v142
	s_nop 1
	v_permlane16_swap_b32_e32 v142, v143
	v_add_f32_e32 v142, v142, v143
	v_mov_b32_e32 v143, v142
	s_nop 1
	v_permlane32_swap_b32_e32 v142, v143
	v_add_f32_e32 v142, v142, v143
	v_fmamk_f32 v142, v142, 0x3a000000, v174
	v_mul_f32_e32 v143, 0x4b800000, v142
	v_cmp_gt_f32_e32 vcc, s9, v142
	s_nop 1
	v_cndmask_b32_e32 v142, v142, v143, vcc
	v_rsq_f32_e32 v142, v142
	s_nop 0
	v_mul_f32_e32 v143, 0x45800000, v142
	v_cndmask_b32_e32 v142, v142, v143, vcc
	v_pk_mul_f32 v[38:39], v[38:39], v[142:143] op_sel_hi:[1,0]
	v_pk_mul_f32 v[36:37], v[36:37], v[142:143] op_sel_hi:[1,0]
	v_pk_mul_f32 v[30:31], v[30:31], v[142:143] op_sel_hi:[1,0]
	v_pk_mul_f32 v[28:29], v[28:29], v[142:143] op_sel_hi:[1,0]
	v_pk_mul_f32 v[22:23], v[22:23], v[142:143] op_sel_hi:[1,0]
	v_pk_mul_f32 v[20:21], v[20:21], v[142:143] op_sel_hi:[1,0]
	v_pk_mul_f32 v[18:19], v[18:19], v[142:143] op_sel_hi:[1,0]
	v_pk_mul_f32 v[16:17], v[16:17], v[142:143] op_sel_hi:[1,0]
	v_pk_mul_f32 v[46:47], v[46:47], v[142:143] op_sel_hi:[1,0]
	v_pk_mul_f32 v[44:45], v[44:45], v[142:143] op_sel_hi:[1,0]
	v_pk_mul_f32 v[42:43], v[42:43], v[142:143] op_sel_hi:[1,0]
	v_pk_mul_f32 v[40:41], v[40:41], v[142:143] op_sel_hi:[1,0]
	v_pk_mul_f32 v[34:35], v[34:35], v[142:143] op_sel_hi:[1,0]
	v_pk_mul_f32 v[32:33], v[32:33], v[142:143] op_sel_hi:[1,0]
	v_pk_mul_f32 v[26:27], v[26:27], v[142:143] op_sel_hi:[1,0]
	v_pk_mul_f32 v[24:25], v[24:25], v[142:143] op_sel_hi:[1,0]
	v_pk_mul_f32 v[36:37], v[48:49], v[36:37]
	v_pk_mul_f32 v[38:39], v[50:51], v[38:39]
	v_pk_mul_f32 v[28:29], v[52:53], v[28:29]
	v_pk_mul_f32 v[30:31], v[54:55], v[30:31]
	v_pk_mul_f32 v[20:21], v[56:57], v[20:21]
	v_pk_mul_f32 v[22:23], v[58:59], v[22:23]
	v_pk_mul_f32 v[16:17], v[60:61], v[16:17]
	v_pk_mul_f32 v[18:19], v[62:63], v[18:19]
	v_pk_mul_f32 v[44:45], v[80:81], v[44:45]
	v_pk_mul_f32 v[46:47], v[82:83], v[46:47]
	v_pk_mul_f32 v[40:41], v[84:85], v[40:41]
	v_pk_mul_f32 v[42:43], v[86:87], v[42:43]
	v_pk_mul_f32 v[32:33], v[88:89], v[32:33]
	v_pk_mul_f32 v[34:35], v[90:91], v[34:35]
	v_pk_mul_f32 v[24:25], v[92:93], v[24:25]
	v_pk_mul_f32 v[26:27], v[94:95], v[26:27]
	v_pk_fma_f32 v[6:7], v[162:163], v[38:39], v[6:7]
	v_pk_fma_f32 v[4:5], v[164:165], v[36:37], v[4:5]
	v_pk_fma_f32 v[2:3], v[122:123], v[30:31], v[2:3]
	v_pk_fma_f32 v[0:1], v[120:121], v[28:29], v[0:1]
	v_pk_fma_f32 v[14:15], v[118:119], v[22:23], v[14:15]
	v_pk_fma_f32 v[12:13], v[116:117], v[20:21], v[12:13]
	v_pk_fma_f32 v[10:11], v[114:115], v[18:19], v[10:11]
	v_pk_fma_f32 v[8:9], v[112:113], v[16:17], v[8:9]
	v_pk_fma_f32 v[16:17], v[110:111], v[46:47], v[70:71]
	v_pk_fma_f32 v[18:19], v[108:109], v[44:45], v[68:69]
	v_pk_fma_f32 v[20:21], v[106:107], v[42:43], v[66:67]
	v_pk_fma_f32 v[22:23], v[104:105], v[40:41], v[64:65]
	s_waitcnt vmcnt(1)
	v_pk_fma_f32 v[28:29], v[102:103], v[34:35], v[78:79]
	v_pk_fma_f32 v[30:31], v[100:101], v[32:33], v[76:77]
	s_waitcnt vmcnt(0)
	v_pk_fma_f32 v[26:27], v[98:99], v[26:27], v[74:75]
	v_pk_fma_f32 v[24:25], v[96:97], v[24:25], v[72:73]
	v_bfe_u32 v32, v4, 16, 1
	v_bfe_u32 v34, v6, 16, 1
	v_bfe_u32 v33, v5, 16, 1
	v_bfe_u32 v35, v7, 16, 1
	v_bfe_u32 v36, v0, 16, 1
	v_bfe_u32 v37, v1, 16, 1
	v_bfe_u32 v38, v2, 16, 1
	v_bfe_u32 v40, v12, 16, 1
	v_bfe_u32 v41, v13, 16, 1
	v_bfe_u32 v42, v14, 16, 1
	v_bfe_u32 v43, v15, 16, 1
	v_bfe_u32 v44, v8, 16, 1
	v_bfe_u32 v46, v10, 16, 1
	v_bfe_u32 v48, v18, 16, 1
	v_bfe_u32 v49, v19, 16, 1
	v_bfe_u32 v50, v16, 16, 1
	v_bfe_u32 v52, v22, 16, 1
	v_bfe_u32 v53, v23, 16, 1
	v_bfe_u32 v54, v20, 16, 1
	v_bfe_u32 v56, v30, 16, 1
	v_bfe_u32 v58, v28, 16, 1
	v_bfe_u32 v60, v24, 16, 1
	v_bfe_u32 v62, v26, 16, 1
	v_add3_u32 v4, v4, v32, s10
	v_add3_u32 v6, v6, v34, s10
	v_bfe_u32 v39, v3, 16, 1
	v_bfe_u32 v45, v9, 16, 1
	v_bfe_u32 v47, v11, 16, 1
	v_bfe_u32 v51, v17, 16, 1
	v_bfe_u32 v55, v21, 16, 1
	v_bfe_u32 v57, v31, 16, 1
	v_bfe_u32 v59, v29, 16, 1
	v_bfe_u32 v61, v25, 16, 1
	v_bfe_u32 v63, v27, 16, 1
	v_add3_u32 v5, v5, v33, s10
	v_add3_u32 v7, v7, v35, s10
	v_add3_u32 v0, v0, v36, s10
	v_add3_u32 v32, v1, v37, s10
	v_add3_u32 v1, v2, v38, s10
	v_add3_u32 v2, v12, v40, s10
	v_add3_u32 v12, v13, v41, s10
	v_add3_u32 v13, v14, v42, s10
	v_add3_u32 v14, v15, v43, s10
	v_add3_u32 v8, v8, v44, s10
	v_add3_u32 v10, v10, v46, s10
	v_add3_u32 v15, v18, v48, s10
	v_add3_u32 v18, v19, v49, s10
	v_add3_u32 v16, v16, v50, s10
	v_add3_u32 v19, v22, v52, s10
	v_add3_u32 v22, v23, v53, s10
	v_add3_u32 v20, v20, v54, s10
	v_add3_u32 v23, v30, v56, s10
	v_add3_u32 v28, v28, v58, s10
	v_add3_u32 v24, v24, v60, s10
	v_add3_u32 v26, v26, v62, s10
	v_lshrrev_b32_e32 v4, 16, v4
	v_lshrrev_b32_e32 v6, 16, v6
	v_add3_u32 v3, v3, v39, s10
	v_add3_u32 v9, v9, v45, s10
	v_add3_u32 v11, v11, v47, s10
	v_add3_u32 v17, v17, v51, s10
	v_add3_u32 v21, v21, v55, s10
	v_add3_u32 v30, v31, v57, s10
	v_add3_u32 v29, v29, v59, s10
	v_add3_u32 v25, v25, v61, s10
	v_add3_u32 v27, v27, v63, s10
	v_lshrrev_b32_e32 v31, 16, v0
	v_lshrrev_b32_e32 v33, 16, v1
	v_lshrrev_b32_e32 v34, 16, v2
	v_lshrrev_b32_e32 v13, 16, v13
	v_lshrrev_b32_e32 v8, 16, v8
	v_lshrrev_b32_e32 v10, 16, v10
	v_lshrrev_b32_e32 v15, 16, v15
	v_lshrrev_b32_e32 v16, 16, v16
	v_lshrrev_b32_e32 v19, 16, v19
	v_lshrrev_b32_e32 v20, 16, v20
	v_lshrrev_b32_e32 v23, 16, v23
	v_lshrrev_b32_e32 v28, 16, v28
	v_lshrrev_b32_e32 v24, 16, v24
	v_lshrrev_b32_e32 v26, 16, v26
	v_and_or_b32 v0, v5, s11, v4
	v_and_or_b32 v1, v7, s11, v6
	v_and_or_b32 v2, v32, s11, v31
	v_and_or_b32 v3, v3, s11, v33
	v_and_or_b32 v4, v12, s11, v34
	v_and_or_b32 v5, v14, s11, v13
	v_and_or_b32 v6, v9, s11, v8
	v_and_or_b32 v7, v11, s11, v10
	v_and_or_b32 v8, v18, s11, v15
	v_and_or_b32 v9, v17, s11, v16
	v_and_or_b32 v10, v22, s11, v19
	v_and_or_b32 v11, v21, s11, v20
	v_and_or_b32 v12, v30, s11, v23
	v_and_or_b32 v13, v29, s11, v28
	v_and_or_b32 v14, v25, s11, v24
	v_and_or_b32 v15, v27, s11, v26
	global_store_dwordx2 v[140:141], v[0:1], off offset:-3584
	global_store_dwordx2 v[140:141], v[2:3], off offset:-3072
	global_store_dwordx2 v[140:141], v[4:5], off offset:-2560
	global_store_dwordx2 v[140:141], v[6:7], off offset:-2048
	global_store_dwordx2 v[140:141], v[8:9], off offset:-1536
	global_store_dwordx2 v[140:141], v[10:11], off offset:-1024
	global_store_dwordx2 v[140:141], v[12:13], off offset:-512
	global_store_dwordx2 v[140:141], v[14:15], off
	v_lshl_add_u64 v[140:141], v[140:141], 0, s[6:7]
	s_cbranch_scc0 .LBB0_119

.LBB0_921:
	s_waitcnt vmcnt(7)
	v_and_b32_e32 v181, 0xffff0000, v208
	v_and_b32_e32 v183, 0xffff0000, v209
	v_lshlrev_b32_e32 v180, 16, v208
	v_lshlrev_b32_e32 v182, 16, v209
	v_mul_f32_e32 v208, v183, v183
	s_waitcnt vmcnt(6)
	v_lshlrev_b32_e32 v211, 16, v207
	v_lshlrev_b32_e32 v210, 16, v206
	v_and_b32_e32 v207, 0xffff0000, v207
	v_and_b32_e32 v206, 0xffff0000, v206
	s_waitcnt vmcnt(4)
	v_lshlrev_b32_e32 v233, 16, v202
	v_mul_f32_e32 v232, v181, v181
	v_pk_fma_f32 v[208:209], v[182:183], v[182:183], v[208:209] op_sel_hi:[1,1,0]
	v_pk_mul_f32 v[212:213], v[206:207], v[206:207]
	v_pk_fma_f32 v[236:237], v[180:181], v[180:181], v[232:233] op_sel_hi:[1,1,0]
	v_pk_fma_f32 v[212:213], v[210:211], v[210:211], v[212:213]
	v_and_b32_e32 v235, 0xffff0000, v202
	v_mov_b32_e32 v232, v236
	v_mov_b32_e32 v238, v208
	v_mov_b32_e32 v239, v233
	v_mul_f32_e32 v234, v235, v235
	v_pk_add_f32 v[208:209], v[236:237], v[208:209]
	v_pk_mul_f32 v[236:237], v[232:233], v[238:239]
	v_pk_add_f32 v[212:213], v[212:213], v[212:213] op_sel:[0,1] op_sel_hi:[1,0]
	v_lshlrev_b32_e32 v230, 16, v204
	v_and_b32_e32 v231, 0xffff0000, v204
	v_lshlrev_b32_e32 v204, 16, v205
	v_and_b32_e32 v205, 0xffff0000, v205
	v_mov_b32_e32 v209, v237
	v_mov_b32_e32 v213, v234
	v_lshlrev_b32_e32 v202, 16, v203
	v_and_b32_e32 v203, 0xffff0000, v203
	v_pk_add_f32 v[208:209], v[208:209], v[212:213]
	v_mul_f32_e32 v212, v231, v231
	v_mul_f32_e32 v232, v205, v205
	v_mul_f32_e32 v240, v202, v202
	v_mul_f32_e32 v241, v203, v203
	v_pk_fma_f32 v[212:213], v[230:231], v[230:231], v[212:213] op_sel_hi:[1,1,0]
	v_pk_fma_f32 v[236:237], v[204:205], v[204:205], v[232:233] op_sel_hi:[1,1,0]
	v_mov_b32_e32 v213, v240
	v_mov_b32_e32 v237, v241
	v_pk_add_f32 v[212:213], v[212:213], v[236:237]
	s_waitcnt vmcnt(2)
	v_lshlrev_b32_e32 v239, 16, v199
	v_pk_add_f32 v[208:209], v[208:209], v[212:213]
	v_lshlrev_b32_e32 v213, 16, v201
	v_lshlrev_b32_e32 v212, 16, v200
	v_and_b32_e32 v201, 0xffff0000, v201
	v_and_b32_e32 v200, 0xffff0000, v200
	v_pk_mul_f32 v[236:237], v[200:201], v[200:201]
	v_lshlrev_b32_e32 v238, 16, v198
	v_pk_fma_f32 v[236:237], v[212:213], v[212:213], v[236:237]
	v_and_b32_e32 v199, 0xffff0000, v199
	v_pk_add_f32 v[236:237], v[236:237], v[236:237] op_sel:[0,1] op_sel_hi:[1,0]
	v_and_b32_e32 v198, 0xffff0000, v198
	s_waitcnt vmcnt(0)
	v_lshlrev_b32_e32 v245, 16, v194
	v_pk_add_f32 v[208:209], v[208:209], v[208:209] op_sel:[0,1] op_sel_hi:[1,0]
	v_pk_mul_f32 v[240:241], v[198:199], v[198:199]
	v_mov_b32_e32 v244, v208
	v_mov_b32_e32 v248, v236
	v_mov_b32_e32 v249, v245
	v_pk_fma_f32 v[240:241], v[238:239], v[238:239], v[240:241]
	v_and_b32_e32 v247, 0xffff0000, v194
	v_pk_add_f32 v[208:209], v[208:209], v[236:237]
	v_pk_mul_f32 v[236:237], v[244:245], v[248:249]
	v_and_b32_e32 v243, 0xffff0000, v196
	v_mul_f32_e32 v232, v247, v247
	v_mov_b32_e32 v209, v237
	v_pk_add_f32 v[236:237], v[240:241], v[240:241] op_sel:[0,1] op_sel_hi:[1,0]
	v_lshlrev_b32_e32 v242, 16, v196
	v_lshlrev_b32_e32 v196, 16, v197
	v_and_b32_e32 v197, 0xffff0000, v197
	v_mov_b32_e32 v237, v232
	v_mul_f32_e32 v232, v243, v243
	v_lshlrev_b32_e32 v194, 16, v195
	v_and_b32_e32 v195, 0xffff0000, v195
	v_pk_add_f32 v[208:209], v[208:209], v[236:237]
	v_pk_fma_f32 v[236:237], v[242:243], v[242:243], v[232:233] op_sel_hi:[1,1,0]
	v_mul_f32_e32 v232, v197, v197
	v_mul_f32_e32 v234, v194, v194
	v_mul_f32_e32 v246, v195, v195
	v_pk_fma_f32 v[240:241], v[196:197], v[196:197], v[232:233] op_sel_hi:[1,1,0]
	v_mov_b32_e32 v237, v234
	v_mov_b32_e32 v241, v246
	v_pk_add_f32 v[236:237], v[236:237], v[240:241]
	v_mov_b32_e32 v234, v233
	v_pk_add_f32 v[208:209], v[208:209], v[236:237]
	v_mov_b32_e32 v246, v245
	v_add_f32_e32 v208, v208, v209
	s_add_u32 s24, s24, 1
	s_addc_u32 s25, s25, 0
	s_add_u32 s26, s26, 0x1000
	s_addc_u32 s27, s27, 0
	s_waitcnt lgkmcnt(0)
	s_add_i32 s35, s35, 1
	s_cmp_ge_i32 s35, s34
	s_waitcnt lgkmcnt(0)
	s_waitcnt lgkmcnt(0)
	s_waitcnt lgkmcnt(0)
	s_waitcnt lgkmcnt(0)
	s_waitcnt lgkmcnt(0)
	s_nop 1
	v_add_f32_dpp v208, v208, v208 quad_perm:[1,0,3,2] row_mask:0xf bank_mask:0xf
	s_nop 1
	v_add_f32_dpp v208, v208, v208 quad_perm:[2,3,0,1] row_mask:0xf bank_mask:0xf
	s_nop 1
	v_add_f32_dpp v208, v208, v208 row_half_mirror row_mask:0xf bank_mask:0xf
	s_nop 1
	v_add_f32_dpp v208, v208, v208 row_mirror row_mask:0xf bank_mask:0xf
	v_mov_b32_e32 v209, v208
	s_nop 1
	v_permlane16_swap_b32_e32 v208, v209
	v_add_f32_e32 v208, v208, v209
	v_mov_b32_e32 v209, v208
	s_nop 1
	v_permlane32_swap_b32_e32 v208, v209
	v_add_f32_e32 v208, v208, v209
	v_fmamk_f32 v208, v208, 0x3a000000, v252
	v_mul_f32_e32 v209, 0x4b800000, v208
	v_cmp_gt_f32_e32 vcc, s88, v208
	s_nop 1
	v_cndmask_b32_e32 v208, v208, v209, vcc
	v_rsq_f32_e32 v208, v208
	s_nop 0
	v_mul_f32_e32 v209, 0x45800000, v208
	v_cndmask_b32_e32 v208, v208, v209, vcc
	v_pk_mul_f32 v[180:181], v[208:209], v[180:181] op_sel_hi:[0,1]
	v_pk_mul_f32 v[180:181], v[32:33], v[180:181]
	v_pk_mul_f32 v[182:183], v[208:209], v[182:183] op_sel_hi:[0,1]
	v_pk_fma_f32 v[0:1], v[64:65], v[180:181], v[0:1]
	v_mov_b32_e32 v180, v211
	v_mov_b32_e32 v181, v207
	v_pk_mul_f32 v[180:181], v[208:209], v[180:181] op_sel_hi:[0,1]
	v_pk_mul_f32 v[180:181], v[38:39], v[180:181]
	v_pk_mul_f32 v[182:183], v[34:35], v[182:183]
	v_pk_fma_f32 v[6:7], v[70:71], v[180:181], v[6:7]
	v_pk_mul_f32 v[180:181], v[208:209], v[204:205] op_sel_hi:[0,1]
	v_pk_mul_f32 v[180:181], v[42:43], v[180:181]
	v_mov_b32_e32 v211, v206
	v_pk_fma_f32 v[10:11], v[74:75], v[180:181], v[10:11]
	v_pk_mul_f32 v[180:181], v[202:203], v[208:209] op_sel_hi:[1,0]
	v_pk_fma_f32 v[2:3], v[66:67], v[182:183], v[2:3]
	v_pk_mul_f32 v[180:181], v[46:47], v[180:181]
	v_pk_mul_f32 v[182:183], v[208:209], v[210:211] op_sel_hi:[0,1]
	v_pk_fma_f32 v[14:15], v[78:79], v[180:181], v[14:15]
	v_mov_b32_e32 v180, v213
	v_mov_b32_e32 v181, v201
	v_pk_mul_f32 v[182:183], v[36:37], v[182:183]
	v_pk_mul_f32 v[180:181], v[208:209], v[180:181] op_sel_hi:[0,1]
	v_pk_fma_f32 v[4:5], v[68:69], v[182:183], v[4:5]
	v_pk_mul_f32 v[182:183], v[208:209], v[230:231] op_sel_hi:[0,1]
	v_pk_mul_f32 v[180:181], v[50:51], v[180:181]
	v_pk_mul_f32 v[182:183], v[40:41], v[182:183]
	v_pk_fma_f32 v[18:19], v[82:83], v[180:181], v[18:19]
	v_mov_b32_e32 v180, v239
	v_mov_b32_e32 v181, v199
	v_pk_fma_f32 v[8:9], v[72:73], v[182:183], v[8:9]
	v_pk_mul_f32 v[182:183], v[234:235], v[208:209] op_sel_hi:[1,0]
	v_pk_mul_f32 v[180:181], v[208:209], v[180:181] op_sel_hi:[0,1]
	v_pk_mul_f32 v[182:183], v[44:45], v[182:183]
	v_mov_b32_e32 v213, v200
	v_pk_mul_f32 v[180:181], v[54:55], v[180:181]
	v_pk_fma_f32 v[12:13], v[76:77], v[182:183], v[12:13]
	v_pk_mul_f32 v[182:183], v[208:209], v[212:213] op_sel_hi:[0,1]
	v_pk_fma_f32 v[22:23], v[86:87], v[180:181], v[22:23]
	v_pk_mul_f32 v[180:181], v[208:209], v[196:197] op_sel_hi:[0,1]
	v_pk_mul_f32 v[182:183], v[48:49], v[182:183]
	v_mov_b32_e32 v239, v198
	v_pk_mul_f32 v[180:181], v[58:59], v[180:181]
	v_pk_fma_f32 v[16:17], v[80:81], v[182:183], v[16:17]
	v_pk_mul_f32 v[182:183], v[208:209], v[238:239] op_sel_hi:[0,1]
	v_pk_fma_f32 v[26:27], v[90:91], v[180:181], v[26:27]
	v_pk_mul_f32 v[180:181], v[194:195], v[208:209] op_sel_hi:[1,0]
	v_pk_mul_f32 v[182:183], v[52:53], v[182:183]
	v_pk_mul_f32 v[180:181], v[62:63], v[180:181]
	v_pk_fma_f32 v[20:21], v[84:85], v[182:183], v[20:21]
	v_pk_mul_f32 v[182:183], v[208:209], v[242:243] op_sel_hi:[0,1]
	v_pk_fma_f32 v[30:31], v[94:95], v[180:181], v[30:31]
	v_pk_mul_f32 v[182:183], v[56:57], v[182:183]
	v_pk_fma_f32 v[24:25], v[88:89], v[182:183], v[24:25]
	v_pk_mul_f32 v[182:183], v[246:247], v[208:209] op_sel_hi:[1,0]
	v_pk_mul_f32 v[182:183], v[60:61], v[182:183]
	v_cvt_pk_bf16_f32 v180, v0, v1
	v_pk_fma_f32 v[28:29], v[92:93], v[182:183], v[28:29]
	v_lshl_add_u64 v[194:195], v[164:165], 0, s[28:29]
	v_cvt_pk_bf16_f32 v181, v2, v3
	global_store_dwordx2 v[194:195], v[180:181], off
	v_cvt_pk_bf16_f32 v180, v4, v5
	v_cvt_pk_bf16_f32 v181, v6, v7
	global_store_dwordx2 v[194:195], v[180:181], off offset:512
	v_cvt_pk_bf16_f32 v180, v8, v9
	v_cvt_pk_bf16_f32 v181, v10, v11
	global_store_dwordx2 v[194:195], v[180:181], off offset:1024
	v_cvt_pk_bf16_f32 v180, v12, v13
	v_cvt_pk_bf16_f32 v181, v14, v15
	global_store_dwordx2 v[194:195], v[180:181], off offset:1536
	v_cvt_pk_bf16_f32 v180, v16, v17
	v_cvt_pk_bf16_f32 v181, v18, v19
	global_store_dwordx2 v[194:195], v[180:181], off offset:2048
	v_cvt_pk_bf16_f32 v180, v20, v21
	v_mov_b32_e32 v196, v1
	v_mov_b32_e32 v197, v5
	v_cvt_pk_bf16_f32 v181, v22, v23
	v_mov_b32_e32 v182, v0
	v_mov_b32_e32 v183, v4
	v_pk_mul_f32 v[196:197], v[196:197], v[196:197]
	v_mov_b32_e32 v198, v3
	v_mov_b32_e32 v199, v7
	v_pk_fma_f32 v[182:183], v[182:183], v[182:183], v[196:197]
	v_mov_b32_e32 v196, v2
	v_mov_b32_e32 v197, v6
	v_pk_mul_f32 v[198:199], v[198:199], v[198:199]
	global_store_dwordx2 v[194:195], v[180:181], off offset:2560
	v_pk_fma_f32 v[196:197], v[196:197], v[196:197], v[198:199]
	v_pk_mul_f32 v[198:199], v[8:9], v[8:9]
	v_pk_add_f32 v[182:183], v[182:183], v[196:197]
	v_pk_mul_f32 v[196:197], v[10:11], v[10:11]
	v_pk_add_f32 v[182:183], v[182:183], v[182:183] op_sel_hi:[0,1]
	v_pk_mov_b32 v[200:201], v[198:199], v[196:197] op_sel:[1,0]
	v_mov_b32_e32 v199, v197
	v_mul_f32_e32 v182, v12, v12
	v_pk_add_f32 v[196:197], v[200:201], v[198:199]
	v_pk_fma_f32 v[198:199], v[12:13], v[12:13], v[182:183] op_sel_hi:[1,1,0]
	v_mul_f32_e32 v182, v14, v14
	v_pk_add_f32 v[196:197], v[196:197], v[196:197] op_sel_hi:[0,1]
	v_pk_fma_f32 v[200:201], v[14:15], v[14:15], v[182:183] op_sel_hi:[1,1,0]
	v_mul_f32_e32 v198, v16, v16
	v_mul_f32_e32 v200, v17, v17
	v_mul_f32_e32 v196, v18, v18
	v_mul_f32_e32 v182, v19, v19
	v_pk_add_f32 v[198:199], v[198:199], v[200:201]
	v_pk_add_f32 v[182:183], v[196:197], v[182:183]
	v_pk_mul_f32 v[196:197], v[22:23], v[22:23]
	v_pk_add_f32 v[182:183], v[198:199], v[182:183]
	v_pk_mul_f32 v[198:199], v[20:21], v[20:21]
	v_pk_add_f32 v[182:183], v[182:183], v[182:183] op_sel_hi:[0,1]
	v_pk_mov_b32 v[200:201], v[198:199], v[196:197] op_sel:[1,0]
	v_mov_b32_e32 v199, v197
	v_mul_f32_e32 v182, v24, v24
	v_pk_add_f32 v[196:197], v[200:201], v[198:199]
	v_pk_fma_f32 v[198:199], v[24:25], v[24:25], v[182:183] op_sel_hi:[1,1,0]
	v_mul_f32_e32 v182, v26, v26
	v_pk_add_f32 v[196:197], v[196:197], v[196:197] op_sel_hi:[0,1]
	v_pk_fma_f32 v[200:201], v[26:27], v[26:27], v[182:183] op_sel_hi:[1,1,0]
	v_mul_f32_e32 v198, v28, v28
	v_mul_f32_e32 v200, v29, v29
	v_mul_f32_e32 v196, v30, v30
	v_mul_f32_e32 v182, v31, v31
	v_pk_add_f32 v[198:199], v[198:199], v[200:201]
	v_pk_add_f32 v[182:183], v[196:197], v[182:183]
	v_pk_add_f32 v[182:183], v[198:199], v[182:183]
	v_add_f32_e32 v182, v182, v183
	v_mov_b64_e32 v[198:199], v[174:175]
	s_waitcnt lgkmcnt(0)
	v_cvt_pk_bf16_f32 v180, v24, v25
	s_waitcnt lgkmcnt(0)
	v_mov_b64_e32 v[200:201], v[184:185]
	v_mov_b64_e32 v[202:203], v[186:187]
	s_waitcnt lgkmcnt(0)
	v_cvt_pk_bf16_f32 v181, v26, v27
	global_store_dwordx2 v[194:195], v[180:181], off offset:3072
	s_waitcnt lgkmcnt(0)
	v_cvt_pk_bf16_f32 v180, v28, v29
	s_waitcnt lgkmcnt(0)
	s_nop 0
	s_nop 0
	s_waitcnt lgkmcnt(0)
	s_nop 1
	v_add_f32_dpp v181, v182, v182 quad_perm:[1,0,3,2] row_mask:0xf bank_mask:0xf
	s_nop 1
	v_add_f32_dpp v181, v181, v181 quad_perm:[2,3,0,1] row_mask:0xf bank_mask:0xf
	s_nop 1
	v_add_f32_dpp v181, v181, v181 row_half_mirror row_mask:0xf bank_mask:0xf
	s_nop 1
	v_add_f32_dpp v181, v181, v181 row_mirror row_mask:0xf bank_mask:0xf
	v_mov_b32_e32 v182, v181
	s_nop 1
	v_permlane16_swap_b32_e32 v181, v182
	v_add_f32_e32 v181, v181, v182
	v_mov_b32_e32 v182, v181
	s_nop 1
	v_permlane32_swap_b32_e32 v181, v182
	v_add_f32_e32 v181, v181, v182
	v_fmamk_f32 v181, v181, 0x3a000000, v252
	v_mul_f32_e32 v182, 0x4b800000, v181
	v_cmp_gt_f32_e32 vcc, s88, v181
	v_mov_b64_e32 v[204:205], v[188:189]
	v_mov_b64_e32 v[206:207], v[190:191]
	v_cndmask_b32_e32 v181, v181, v182, vcc
	v_rsq_f32_e32 v182, v181
	s_nop 0
	v_cvt_pk_bf16_f32 v181, v30, v31
	global_store_dwordx2 v[194:195], v[180:181], off offset:3584
	v_mul_f32_e32 v180, 0x45800000, v182
	v_cndmask_b32_e32 v180, v182, v180, vcc
	v_pk_mul_f32 v[194:195], v[0:1], v[180:181] op_sel_hi:[1,0]
	v_pk_mul_f32 v[196:197], v[2:3], v[180:181] op_sel_hi:[1,0]
	v_pk_fma_f32 v[194:195], v[132:133], v[194:195], v[96:97]
	v_pk_fma_f32 v[196:197], v[130:131], v[196:197], v[98:99]
	s_nop 0
	s_nop 0
	v_cvt_pk_bf16_f32 v194, v194, v195
	v_lshl_add_u64 v[182:183], v[166:167], 0, s[28:29]
	v_cvt_pk_bf16_f32 v195, v196, v197
	global_store_dwordx2 v[182:183], v[194:195], off
	v_pk_mul_f32 v[194:195], v[4:5], v[180:181] op_sel_hi:[1,0]
	v_pk_mul_f32 v[196:197], v[6:7], v[180:181] op_sel_hi:[1,0]
	v_pk_fma_f32 v[194:195], v[136:137], v[194:195], v[100:101]
	v_pk_fma_f32 v[196:197], v[134:135], v[196:197], v[102:103]
	v_cvt_pk_bf16_f32 v194, v194, v195
	v_cvt_pk_bf16_f32 v195, v196, v197
	global_store_dwordx2 v[182:183], v[194:195], off offset:512
	v_pk_mul_f32 v[194:195], v[8:9], v[180:181] op_sel_hi:[1,0]
	v_pk_mul_f32 v[196:197], v[10:11], v[180:181] op_sel_hi:[1,0]
	v_pk_fma_f32 v[194:195], v[140:141], v[194:195], v[104:105]
	v_pk_fma_f32 v[196:197], v[138:139], v[196:197], v[106:107]
	v_cvt_pk_bf16_f32 v194, v194, v195
	v_cvt_pk_bf16_f32 v195, v196, v197
	global_store_dwordx2 v[182:183], v[194:195], off offset:1024
	v_pk_mul_f32 v[194:195], v[12:13], v[180:181] op_sel_hi:[1,0]
	v_pk_mul_f32 v[196:197], v[14:15], v[180:181] op_sel_hi:[1,0]
	v_pk_fma_f32 v[194:195], v[144:145], v[194:195], v[108:109]
	v_pk_fma_f32 v[196:197], v[142:143], v[196:197], v[110:111]
	v_cvt_pk_bf16_f32 v194, v194, v195
	v_cvt_pk_bf16_f32 v195, v196, v197
	global_store_dwordx2 v[182:183], v[194:195], off offset:1536
	v_pk_mul_f32 v[194:195], v[16:17], v[180:181] op_sel_hi:[1,0]
	v_pk_mul_f32 v[196:197], v[18:19], v[180:181] op_sel_hi:[1,0]
	v_pk_fma_f32 v[194:195], v[148:149], v[194:195], v[112:113]
	v_pk_fma_f32 v[196:197], v[146:147], v[196:197], v[114:115]
	v_cvt_pk_bf16_f32 v194, v194, v195
	v_cvt_pk_bf16_f32 v195, v196, v197
	global_store_dwordx2 v[182:183], v[194:195], off offset:2048
	v_pk_mul_f32 v[194:195], v[20:21], v[180:181] op_sel_hi:[1,0]
	v_pk_mul_f32 v[196:197], v[22:23], v[180:181] op_sel_hi:[1,0]
	v_pk_fma_f32 v[194:195], v[152:153], v[194:195], v[116:117]
	v_pk_fma_f32 v[196:197], v[150:151], v[196:197], v[118:119]
	v_cvt_pk_bf16_f32 v194, v194, v195
	v_cvt_pk_bf16_f32 v195, v196, v197
	global_store_dwordx2 v[182:183], v[194:195], off offset:2560
	v_pk_mul_f32 v[194:195], v[24:25], v[180:181] op_sel_hi:[1,0]
	v_pk_mul_f32 v[196:197], v[26:27], v[180:181] op_sel_hi:[1,0]
	v_pk_fma_f32 v[194:195], v[156:157], v[194:195], v[120:121]
	v_pk_fma_f32 v[196:197], v[154:155], v[196:197], v[122:123]
	v_cvt_pk_bf16_f32 v194, v194, v195
	v_cvt_pk_bf16_f32 v195, v196, v197
	global_store_dwordx2 v[182:183], v[194:195], off offset:3072
	v_pk_mul_f32 v[194:195], v[28:29], v[180:181] op_sel_hi:[1,0]
	v_pk_mul_f32 v[180:181], v[30:31], v[180:181] op_sel_hi:[1,0]
	v_pk_fma_f32 v[194:195], v[160:161], v[194:195], v[124:125]
	v_pk_fma_f32 v[180:181], v[158:159], v[180:181], v[126:127]
	v_cvt_pk_bf16_f32 v194, v194, v195
	v_bfe_u32 v195, v180, 16, 1
	v_add3_u32 v180, v180, v195, s65
	v_bfe_u32 v195, v181, 16, 1
	v_lshrrev_b32_e32 v180, 16, v180
	v_add3_u32 v181, v181, v195, s65
	v_and_or_b32 v195, v181, s61, v180
	global_store_dwordx2 v[182:183], v[194:195], off offset:3584
	v_mov_b64_e32 v[194:195], v[170:171]
	v_mov_b64_e32 v[196:197], v[172:173]
	v_mov_b64_e32 v[208:209], v[192:193]
	s_cbranch_scc1 .LBB0_928

.LBB0_932:
	s_waitcnt vmcnt(23)
	v_lshlrev_b32_e32 v170, 16, v162
	v_and_b32_e32 v171, 0xffff0000, v162
	v_lshlrev_b32_e32 v162, 16, v163
	v_and_b32_e32 v163, 0xffff0000, v163
	v_mul_f32_e32 v172, v163, v163
	s_waitcnt vmcnt(22)
	v_lshlrev_b32_e32 v175, 16, v161
	v_lshlrev_b32_e32 v174, 16, v160
	v_and_b32_e32 v161, 0xffff0000, v161
	v_and_b32_e32 v160, 0xffff0000, v160
	s_waitcnt vmcnt(20)
	v_lshlrev_b32_e32 v185, 16, v156
	v_mul_f32_e32 v184, v171, v171
	v_pk_fma_f32 v[172:173], v[162:163], v[162:163], v[172:173] op_sel_hi:[1,1,0]
	v_pk_mul_f32 v[180:181], v[160:161], v[160:161]
	v_pk_fma_f32 v[188:189], v[170:171], v[170:171], v[184:185] op_sel_hi:[1,1,0]
	v_pk_fma_f32 v[180:181], v[174:175], v[174:175], v[180:181]
	v_and_b32_e32 v187, 0xffff0000, v156
	v_mov_b32_e32 v184, v188
	v_mov_b32_e32 v190, v172
	v_mov_b32_e32 v191, v185
	v_mul_f32_e32 v169, v187, v187
	v_pk_add_f32 v[172:173], v[188:189], v[172:173]
	v_pk_mul_f32 v[188:189], v[184:185], v[190:191]
	v_pk_add_f32 v[180:181], v[180:181], v[180:181] op_sel:[0,1] op_sel_hi:[1,0]
	v_lshlrev_b32_e32 v182, 16, v158
	v_and_b32_e32 v183, 0xffff0000, v158
	v_lshlrev_b32_e32 v158, 16, v159
	v_and_b32_e32 v159, 0xffff0000, v159
	v_mov_b32_e32 v173, v189
	v_mov_b32_e32 v181, v169
	v_lshlrev_b32_e32 v156, 16, v157
	v_and_b32_e32 v157, 0xffff0000, v157
	v_pk_add_f32 v[172:173], v[172:173], v[180:181]
	v_mul_f32_e32 v180, v183, v183
	v_mul_f32_e32 v184, v159, v159
	v_mul_f32_e32 v186, v156, v156
	v_mul_f32_e32 v192, v157, v157
	v_pk_fma_f32 v[180:181], v[182:183], v[182:183], v[180:181] op_sel_hi:[1,1,0]
	v_pk_fma_f32 v[188:189], v[158:159], v[158:159], v[184:185] op_sel_hi:[1,1,0]
	v_mov_b32_e32 v181, v186
	v_mov_b32_e32 v189, v192
	v_pk_add_f32 v[180:181], v[180:181], v[188:189]
	s_waitcnt vmcnt(18)
	v_lshlrev_b32_e32 v191, 16, v153
	v_pk_add_f32 v[172:173], v[172:173], v[180:181]
	v_lshlrev_b32_e32 v181, 16, v155
	v_lshlrev_b32_e32 v180, 16, v154
	v_and_b32_e32 v155, 0xffff0000, v155
	v_and_b32_e32 v154, 0xffff0000, v154
	v_pk_mul_f32 v[188:189], v[154:155], v[154:155]
	v_lshlrev_b32_e32 v190, 16, v152
	v_pk_fma_f32 v[188:189], v[180:181], v[180:181], v[188:189]
	v_and_b32_e32 v153, 0xffff0000, v153
	v_pk_add_f32 v[188:189], v[188:189], v[188:189] op_sel:[0,1] op_sel_hi:[1,0]
	v_and_b32_e32 v152, 0xffff0000, v152
	s_waitcnt vmcnt(16)
	v_lshlrev_b32_e32 v197, 16, v148
	v_pk_add_f32 v[172:173], v[172:173], v[172:173] op_sel:[0,1] op_sel_hi:[1,0]
	v_pk_mul_f32 v[192:193], v[152:153], v[152:153]
	v_mov_b32_e32 v196, v172
	v_mov_b32_e32 v200, v188
	v_mov_b32_e32 v201, v197
	v_pk_fma_f32 v[192:193], v[190:191], v[190:191], v[192:193]
	v_and_b32_e32 v199, 0xffff0000, v148
	v_pk_add_f32 v[172:173], v[172:173], v[188:189]
	v_pk_mul_f32 v[188:189], v[196:197], v[200:201]
	v_and_b32_e32 v195, 0xffff0000, v150
	v_mul_f32_e32 v169, v199, v199
	v_mov_b32_e32 v173, v189
	v_pk_add_f32 v[188:189], v[192:193], v[192:193] op_sel:[0,1] op_sel_hi:[1,0]
	v_lshlrev_b32_e32 v194, 16, v150
	v_lshlrev_b32_e32 v150, 16, v151
	v_and_b32_e32 v151, 0xffff0000, v151
	v_mov_b32_e32 v189, v169
	v_mul_f32_e32 v184, v195, v195
	v_lshlrev_b32_e32 v148, 16, v149
	v_and_b32_e32 v149, 0xffff0000, v149
	v_pk_add_f32 v[172:173], v[172:173], v[188:189]
	v_pk_fma_f32 v[188:189], v[194:195], v[194:195], v[184:185] op_sel_hi:[1,1,0]
	v_mul_f32_e32 v184, v151, v151
	v_mul_f32_e32 v186, v148, v148
	v_mul_f32_e32 v198, v149, v149
	v_pk_fma_f32 v[192:193], v[150:151], v[150:151], v[184:185] op_sel_hi:[1,1,0]
	v_mov_b32_e32 v189, v186
	v_mov_b32_e32 v193, v198
	v_pk_add_f32 v[188:189], v[188:189], v[192:193]
	v_mov_b32_e32 v186, v185
	v_pk_add_f32 v[172:173], v[172:173], v[188:189]
	v_mov_b32_e32 v198, v197
	v_add_f32_e32 v169, v172, v173
	s_waitcnt lgkmcnt(0)
	s_waitcnt lgkmcnt(0)
	s_waitcnt lgkmcnt(0)
	s_waitcnt lgkmcnt(0)
	s_waitcnt lgkmcnt(0)
	s_waitcnt lgkmcnt(0)
	s_nop 1
	v_add_f32_dpp v169, v169, v169 quad_perm:[1,0,3,2] row_mask:0xf bank_mask:0xf
	s_nop 1
	v_add_f32_dpp v169, v169, v169 quad_perm:[2,3,0,1] row_mask:0xf bank_mask:0xf
	s_nop 1
	v_add_f32_dpp v169, v169, v169 row_half_mirror row_mask:0xf bank_mask:0xf
	s_nop 1
	v_add_f32_dpp v169, v169, v169 row_mirror row_mask:0xf bank_mask:0xf
	v_mov_b32_e32 v172, v169
	s_nop 1
	v_permlane16_swap_b32_e32 v169, v172
	v_add_f32_e32 v169, v169, v172
	v_mov_b32_e32 v172, v169
	s_nop 1
	v_permlane32_swap_b32_e32 v169, v172
	v_add_f32_e32 v169, v169, v172
	v_fmamk_f32 v169, v169, 0x3a000000, v252
	v_mul_f32_e32 v172, 0x4b800000, v169
	v_cmp_gt_f32_e32 vcc, s88, v169
	s_nop 1
	v_cndmask_b32_e32 v169, v169, v172, vcc
	v_rsq_f32_e32 v169, v169
	s_nop 0
	v_mul_f32_e32 v172, 0x45800000, v169
	v_cndmask_b32_e32 v172, v169, v172, vcc
	v_pk_mul_f32 v[170:171], v[172:173], v[170:171] op_sel_hi:[0,1]
	v_pk_mul_f32 v[162:163], v[172:173], v[162:163] op_sel_hi:[0,1]
	s_waitcnt vmcnt(15)
	v_pk_mul_f32 v[92:93], v[92:93], v[170:171]
	v_pk_mul_f32 v[94:95], v[94:95], v[162:163]
	s_waitcnt vmcnt(13)
	v_pk_fma_f32 v[0:1], v[88:89], v[92:93], v[0:1]
	v_mov_b32_e32 v88, v175
	v_mov_b32_e32 v175, v160
	v_pk_fma_f32 v[2:3], v[90:91], v[94:95], v[2:3]
	v_mov_b32_e32 v89, v161
	v_pk_mul_f32 v[90:91], v[172:173], v[174:175] op_sel_hi:[0,1]
	v_pk_mul_f32 v[88:89], v[172:173], v[88:89] op_sel_hi:[0,1]
	v_pk_mul_f32 v[84:85], v[84:85], v[90:91]
	v_pk_mul_f32 v[86:87], v[86:87], v[88:89]
	s_waitcnt vmcnt(12)
	v_pk_fma_f32 v[4:5], v[80:81], v[84:85], v[4:5]
	v_pk_mul_f32 v[80:81], v[172:173], v[158:159] op_sel_hi:[0,1]
	v_pk_fma_f32 v[6:7], v[82:83], v[86:87], v[6:7]
	v_pk_mul_f32 v[82:83], v[172:173], v[182:183] op_sel_hi:[0,1]
	s_waitcnt vmcnt(11)
	v_pk_mul_f32 v[78:79], v[78:79], v[80:81]
	v_pk_mul_f32 v[76:77], v[76:77], v[82:83]
	s_waitcnt vmcnt(9)
	v_pk_fma_f32 v[10:11], v[74:75], v[78:79], v[10:11]
	v_pk_mul_f32 v[74:75], v[186:187], v[172:173] op_sel_hi:[1,0]
	v_pk_fma_f32 v[8:9], v[72:73], v[76:77], v[8:9]
	v_pk_mul_f32 v[72:73], v[156:157], v[172:173] op_sel_hi:[1,0]
	v_pk_mul_f32 v[68:69], v[68:69], v[74:75]
	v_pk_mul_f32 v[70:71], v[70:71], v[72:73]
	s_waitcnt vmcnt(8)
	v_pk_fma_f32 v[12:13], v[64:65], v[68:69], v[12:13]
	v_mov_b32_e32 v64, v181
	v_mov_b32_e32 v181, v154
	v_pk_fma_f32 v[14:15], v[66:67], v[70:71], v[14:15]
	v_pk_mul_f32 v[66:67], v[172:173], v[180:181] op_sel_hi:[0,1]
	s_waitcnt vmcnt(7)
	v_pk_mul_f32 v[60:61], v[60:61], v[66:67]
	v_mov_b32_e32 v65, v155
	s_waitcnt vmcnt(5)
	v_pk_fma_f32 v[16:17], v[56:57], v[60:61], v[16:17]
	v_mov_b32_e32 v56, v191
	v_mov_b32_e32 v57, v153
	v_pk_mul_f32 v[56:57], v[172:173], v[56:57] op_sel_hi:[0,1]
	v_pk_mul_f32 v[54:55], v[54:55], v[56:57]
	v_pk_mul_f32 v[64:65], v[172:173], v[64:65] op_sel_hi:[0,1]
	s_waitcnt vmcnt(4)
	v_pk_fma_f32 v[22:23], v[50:51], v[54:55], v[22:23]
	v_pk_mul_f32 v[50:51], v[172:173], v[194:195] op_sel_hi:[0,1]
	v_pk_mul_f32 v[62:63], v[62:63], v[64:65]
	v_mov_b32_e32 v191, v152
	s_waitcnt vmcnt(3)
	v_pk_mul_f32 v[44:45], v[44:45], v[50:51]
	v_pk_fma_f32 v[18:19], v[58:59], v[62:63], v[18:19]
	v_pk_mul_f32 v[58:59], v[172:173], v[190:191] op_sel_hi:[0,1]
	s_waitcnt vmcnt(1)
	v_pk_fma_f32 v[24:25], v[40:41], v[44:45], v[24:25]
	v_pk_mul_f32 v[40:41], v[148:149], v[172:173] op_sel_hi:[1,0]
	v_pk_mul_f32 v[52:53], v[52:53], v[58:59]
	v_pk_mul_f32 v[38:39], v[38:39], v[40:41]
	v_pk_fma_f32 v[20:21], v[48:49], v[52:53], v[20:21]
	v_pk_mul_f32 v[48:49], v[172:173], v[150:151] op_sel_hi:[0,1]
	s_waitcnt vmcnt(0)
	v_pk_fma_f32 v[30:31], v[34:35], v[38:39], v[30:31]
	v_pk_mul_f32 v[46:47], v[46:47], v[48:49]
	v_pk_fma_f32 v[26:27], v[42:43], v[46:47], v[26:27]
	v_pk_mul_f32 v[42:43], v[198:199], v[172:173] op_sel_hi:[1,0]
	v_pk_mul_f32 v[36:37], v[36:37], v[42:43]
	v_cvt_pk_bf16_f32 v34, v0, v1
	v_pk_fma_f32 v[28:29], v[32:33], v[36:37], v[28:29]
	v_lshl_add_u64 v[32:33], v[98:99], 0, s[12:13]
	v_cvt_pk_bf16_f32 v35, v2, v3
	global_store_dwordx2 v[32:33], v[34:35], off
	v_cvt_pk_bf16_f32 v34, v4, v5
	v_cvt_pk_bf16_f32 v35, v6, v7
	global_store_dwordx2 v[32:33], v[34:35], off offset:512
	v_cvt_pk_bf16_f32 v34, v8, v9
	v_cvt_pk_bf16_f32 v35, v10, v11
	global_store_dwordx2 v[32:33], v[34:35], off offset:1024
	v_cvt_pk_bf16_f32 v34, v12, v13
	v_cvt_pk_bf16_f32 v35, v14, v15
	global_store_dwordx2 v[32:33], v[34:35], off offset:1536
	v_cvt_pk_bf16_f32 v34, v16, v17
	v_cvt_pk_bf16_f32 v35, v18, v19
	global_store_dwordx2 v[32:33], v[34:35], off offset:2048
	v_cvt_pk_bf16_f32 v34, v20, v21
	v_cvt_pk_bf16_f32 v35, v22, v23
	global_store_dwordx2 v[32:33], v[34:35], off offset:2560
	v_cvt_pk_bf16_f32 v34, v24, v25
	v_cvt_pk_bf16_f32 v35, v26, v27
	global_store_dwordx2 v[32:33], v[34:35], off offset:3072
	v_cvt_pk_bf16_f32 v34, v28, v29
	v_cvt_pk_bf16_f32 v35, v30, v31
	global_store_dwordx2 v[32:33], v[34:35], off offset:3584
	v_mad_i64_i32 v[32:33], s[16:17], s14, v224, v[126:127]
	v_mad_i64_i32 v[34:35], s[14:15], s14, v224, v[130:131]
	s_movk_i32 s14, 0x1000
	global_load_dwordx4 v[68:71], v[102:103], off
	global_load_dwordx4 v[72:75], v[102:103], off offset:1024
	global_load_dwordx4 v[76:79], v[32:33], off
	global_load_dwordx4 v[80:83], v[32:33], off offset:1024
	global_load_dwordx4 v[84:87], v[34:35], off
	global_load_dwordx4 v[88:91], v[34:35], off offset:1024
	global_load_dwordx4 v[92:95], v[102:103], off offset:2048
	global_load_dwordx4 v[148:151], v[102:103], off offset:3072
	global_load_dwordx4 v[152:155], v[32:33], off offset:2048
	global_load_dwordx4 v[156:159], v[32:33], off offset:3072
	global_load_dwordx4 v[160:163], v[34:35], off offset:2048
	global_load_dwordx4 v[170:173], v[34:35], off offset:3072
	v_add_co_u32_e32 v32, vcc, s14, v32
	s_nop 1
	v_addc_co_u32_e32 v33, vcc, 0, v33, vcc
	v_add_co_u32_e32 v34, vcc, s14, v34
	s_nop 1
	v_addc_co_u32_e32 v35, vcc, 0, v35, vcc
	global_load_dwordx4 v[180:183], v[114:115], off
	global_load_dwordx4 v[64:67], v[116:117], off
	global_load_dwordx4 v[184:187], v[32:33], off
	global_load_dwordx4 v[60:63], v[32:33], off offset:1024
	global_load_dwordx4 v[188:191], v[34:35], off
	global_load_dwordx4 v[56:59], v[34:35], off offset:1024
	global_load_dwordx4 v[48:51], v[118:119], off
	global_load_dwordx4 v[40:43], v[120:121], off
	global_load_dwordx4 v[52:55], v[32:33], off offset:2048
	global_load_dwordx4 v[36:39], v[32:33], off offset:3072
	global_load_dwordx4 v[44:47], v[34:35], off offset:2048
	s_nop 0
	global_load_dwordx4 v[32:35], v[34:35], off offset:3072
	v_mov_b32_e32 v192, v1
	v_mov_b32_e32 v193, v5
	v_mov_b32_e32 v174, v0
	v_mov_b32_e32 v175, v4
	v_pk_mul_f32 v[192:193], v[192:193], v[192:193]
	v_mov_b32_e32 v194, v3
	v_mov_b32_e32 v195, v7
	v_pk_fma_f32 v[174:175], v[174:175], v[174:175], v[192:193]
	v_mov_b32_e32 v192, v2
	v_mov_b32_e32 v193, v6
	v_pk_mul_f32 v[194:195], v[194:195], v[194:195]
	s_waitcnt vmcnt(21)
	v_pk_add_f32 v[76:77], v[76:77], 1.0 op_sel_hi:[1,0]
	v_pk_fma_f32 v[192:193], v[192:193], v[192:193], v[194:195]
	v_pk_mul_f32 v[194:195], v[8:9], v[8:9]
	v_pk_add_f32 v[174:175], v[174:175], v[192:193]
	v_pk_mul_f32 v[192:193], v[10:11], v[10:11]
	v_pk_add_f32 v[174:175], v[174:175], v[174:175] op_sel_hi:[0,1]
	v_pk_mov_b32 v[196:197], v[194:195], v[192:193] op_sel:[1,0]
	v_mov_b32_e32 v195, v193
	v_mul_f32_e32 v174, v12, v12
	v_pk_add_f32 v[192:193], v[196:197], v[194:195]
	v_pk_fma_f32 v[194:195], v[12:13], v[12:13], v[174:175] op_sel_hi:[1,1,0]
	v_mul_f32_e32 v174, v14, v14
	v_pk_add_f32 v[192:193], v[192:193], v[192:193] op_sel_hi:[0,1]
	v_pk_fma_f32 v[196:197], v[14:15], v[14:15], v[174:175] op_sel_hi:[1,1,0]
	v_mul_f32_e32 v194, v16, v16
	v_mul_f32_e32 v196, v17, v17
	v_mul_f32_e32 v192, v18, v18
	v_mul_f32_e32 v174, v19, v19
	v_pk_add_f32 v[194:195], v[194:195], v[196:197]
	v_pk_add_f32 v[174:175], v[192:193], v[174:175]
	v_pk_mul_f32 v[192:193], v[22:23], v[22:23]
	v_pk_add_f32 v[174:175], v[194:195], v[174:175]
	v_pk_mul_f32 v[194:195], v[20:21], v[20:21]
	v_pk_add_f32 v[174:175], v[174:175], v[174:175] op_sel_hi:[0,1]
	v_pk_mov_b32 v[196:197], v[194:195], v[192:193] op_sel:[1,0]
	v_mov_b32_e32 v195, v193
	v_mul_f32_e32 v174, v24, v24
	v_pk_add_f32 v[192:193], v[196:197], v[194:195]
	v_pk_fma_f32 v[194:195], v[24:25], v[24:25], v[174:175] op_sel_hi:[1,1,0]
	v_mul_f32_e32 v174, v26, v26
	v_pk_add_f32 v[192:193], v[192:193], v[192:193] op_sel_hi:[0,1]
	v_pk_fma_f32 v[196:197], v[26:27], v[26:27], v[174:175] op_sel_hi:[1,1,0]
	v_mul_f32_e32 v194, v28, v28
	v_mul_f32_e32 v196, v29, v29
	v_mul_f32_e32 v192, v30, v30
	v_mul_f32_e32 v174, v31, v31
	v_pk_add_f32 v[194:195], v[194:195], v[196:197]
	v_pk_add_f32 v[174:175], v[192:193], v[174:175]
	v_pk_add_f32 v[78:79], v[78:79], 1.0 op_sel_hi:[1,0]
	v_pk_add_f32 v[174:175], v[194:195], v[174:175]
	v_lshl_add_u64 v[192:193], v[104:105], 0, s[12:13]
	v_add_f32_e32 v169, v174, v175
	s_waitcnt vmcnt(8)
	v_pk_add_f32 v[60:61], v[60:61], 1.0 op_sel_hi:[1,0]
	v_pk_add_f32 v[62:63], v[62:63], 1.0 op_sel_hi:[1,0]
	s_waitcnt vmcnt(3)
	v_pk_add_f32 v[52:53], v[52:53], 1.0 op_sel_hi:[1,0]
	v_pk_add_f32 v[54:55], v[54:55], 1.0 op_sel_hi:[1,0]
	s_waitcnt lgkmcnt(0)
	s_waitcnt vmcnt(2)
	v_pk_add_f32 v[36:37], v[36:37], 1.0 op_sel_hi:[1,0]
	v_pk_add_f32 v[38:39], v[38:39], 1.0 op_sel_hi:[1,0]
	v_readlane_b32 s12, v254, 11
	v_readlane_b32 s13, v254, 12
	s_waitcnt lgkmcnt(0)
	s_add_u32 s24, s24, s12
	s_addc_u32 s25, s25, s13
	v_readlane_b32 s12, v254, 9
	v_readlane_b32 s13, v254, 10
	s_waitcnt lgkmcnt(0)
	s_add_u32 s10, s10, s12
	s_addc_u32 s11, s11, s13
	s_cmpk_gt_i32 s24, 0x3fff
	s_waitcnt lgkmcnt(0)
	s_waitcnt lgkmcnt(0)
	s_waitcnt lgkmcnt(0)
	s_nop 1
	v_add_f32_dpp v169, v169, v169 quad_perm:[1,0,3,2] row_mask:0xf bank_mask:0xf
	s_nop 1
	v_add_f32_dpp v169, v169, v169 quad_perm:[2,3,0,1] row_mask:0xf bank_mask:0xf
	s_nop 1
	v_add_f32_dpp v169, v169, v169 row_half_mirror row_mask:0xf bank_mask:0xf
	s_nop 1
	v_add_f32_dpp v169, v169, v169 row_mirror row_mask:0xf bank_mask:0xf
	v_mov_b32_e32 v174, v169
	s_nop 1
	v_permlane16_swap_b32_e32 v169, v174
	v_add_f32_e32 v169, v169, v174
	v_mov_b32_e32 v174, v169
	s_nop 1
	v_permlane32_swap_b32_e32 v169, v174
	v_add_f32_e32 v169, v169, v174
	v_fmamk_f32 v169, v169, 0x3a000000, v252
	v_mul_f32_e32 v174, 0x4b800000, v169
	v_cmp_gt_f32_e32 vcc, s88, v169
	s_nop 1
	v_cndmask_b32_e32 v169, v169, v174, vcc
	v_rsq_f32_e32 v169, v169
	s_nop 0
	v_mul_f32_e32 v174, 0x45800000, v169
	v_cndmask_b32_e32 v174, v169, v174, vcc
	v_pk_mul_f32 v[196:197], v[0:1], v[174:175] op_sel_hi:[1,0]
	v_pk_mul_f32 v[194:195], v[2:3], v[174:175] op_sel_hi:[1,0]
	v_pk_mul_f32 v[68:69], v[68:69], v[196:197]
	v_pk_mul_f32 v[70:71], v[70:71], v[194:195]
	v_pk_fma_f32 v[68:69], v[76:77], v[68:69], v[84:85]
	v_pk_fma_f32 v[70:71], v[78:79], v[70:71], v[86:87]
	v_bfe_u32 v76, v68, 16, 1
	v_add3_u32 v68, v68, v76, s65
	v_bfe_u32 v76, v69, 16, 1
	v_lshrrev_b32_e32 v68, 16, v68
	v_add3_u32 v69, v69, v76, s65
	v_and_or_b32 v68, v69, s61, v68
	v_cvt_pk_bf16_f32 v69, v70, v71
	global_store_dwordx2 v[192:193], v[68:69], off
	v_pk_mul_f32 v[68:69], v[6:7], v[174:175] op_sel_hi:[1,0]
	v_pk_mul_f32 v[70:71], v[4:5], v[174:175] op_sel_hi:[1,0]
	v_pk_mul_f32 v[68:69], v[74:75], v[68:69]
	v_pk_mul_f32 v[70:71], v[72:73], v[70:71]
	v_pk_add_f32 v[74:75], v[80:81], 1.0 op_sel_hi:[1,0]
	v_pk_add_f32 v[72:73], v[82:83], 1.0 op_sel_hi:[1,0]
	v_pk_fma_f32 v[70:71], v[74:75], v[70:71], v[88:89]
	v_pk_fma_f32 v[68:69], v[72:73], v[68:69], v[90:91]
	v_cvt_pk_bf16_f32 v70, v70, v71
	v_cvt_pk_bf16_f32 v71, v68, v69
	global_store_dwordx2 v[192:193], v[70:71], off offset:512
	v_pk_mul_f32 v[70:71], v[8:9], v[174:175] op_sel_hi:[1,0]
	v_pk_mul_f32 v[68:69], v[10:11], v[174:175] op_sel_hi:[1,0]
	v_pk_mul_f32 v[70:71], v[92:93], v[70:71]
	v_pk_add_f32 v[74:75], v[152:153], 1.0 op_sel_hi:[1,0]
	v_pk_mul_f32 v[68:69], v[94:95], v[68:69]
	v_pk_add_f32 v[72:73], v[154:155], 1.0 op_sel_hi:[1,0]
	v_pk_fma_f32 v[70:71], v[74:75], v[70:71], v[160:161]
	v_pk_fma_f32 v[68:69], v[72:73], v[68:69], v[162:163]
	v_cvt_pk_bf16_f32 v70, v70, v71
	v_cvt_pk_bf16_f32 v71, v68, v69
	global_store_dwordx2 v[192:193], v[70:71], off offset:1024
	v_pk_mul_f32 v[70:71], v[12:13], v[174:175] op_sel_hi:[1,0]
	v_pk_mul_f32 v[68:69], v[14:15], v[174:175] op_sel_hi:[1,0]
	v_pk_mul_f32 v[70:71], v[148:149], v[70:71]
	v_pk_add_f32 v[74:75], v[156:157], 1.0 op_sel_hi:[1,0]
	v_pk_mul_f32 v[68:69], v[150:151], v[68:69]
	v_pk_add_f32 v[72:73], v[158:159], 1.0 op_sel_hi:[1,0]
	v_pk_fma_f32 v[70:71], v[74:75], v[70:71], v[170:171]
	v_pk_fma_f32 v[68:69], v[72:73], v[68:69], v[172:173]
	v_cvt_pk_bf16_f32 v70, v70, v71
	v_cvt_pk_bf16_f32 v71, v68, v69
	global_store_dwordx2 v[192:193], v[70:71], off offset:1536
	v_pk_mul_f32 v[70:71], v[16:17], v[174:175] op_sel_hi:[1,0]
	v_pk_mul_f32 v[68:69], v[18:19], v[174:175] op_sel_hi:[1,0]
	v_pk_mul_f32 v[70:71], v[180:181], v[70:71]
	v_pk_add_f32 v[74:75], v[184:185], 1.0 op_sel_hi:[1,0]
	v_pk_mul_f32 v[68:69], v[182:183], v[68:69]
	v_pk_add_f32 v[72:73], v[186:187], 1.0 op_sel_hi:[1,0]
	v_pk_fma_f32 v[70:71], v[74:75], v[70:71], v[188:189]
	v_pk_fma_f32 v[68:69], v[72:73], v[68:69], v[190:191]
	v_bfe_u32 v72, v70, 16, 1
	v_add3_u32 v70, v70, v72, s65
	v_bfe_u32 v72, v71, 16, 1
	v_lshrrev_b32_e32 v70, 16, v70
	v_add3_u32 v71, v71, v72, s65
	v_and_or_b32 v70, v71, s61, v70
	v_cvt_pk_bf16_f32 v71, v68, v69
	global_store_dwordx2 v[192:193], v[70:71], off offset:2048
	v_pk_mul_f32 v[70:71], v[20:21], v[174:175] op_sel_hi:[1,0]
	v_pk_mul_f32 v[68:69], v[22:23], v[174:175] op_sel_hi:[1,0]
	v_pk_mul_f32 v[64:65], v[64:65], v[70:71]
	v_pk_mul_f32 v[66:67], v[66:67], v[68:69]
	v_pk_fma_f32 v[56:57], v[60:61], v[64:65], v[56:57]
	v_pk_fma_f32 v[58:59], v[62:63], v[66:67], v[58:59]
	v_bfe_u32 v60, v56, 16, 1
	v_add3_u32 v56, v56, v60, s65
	v_bfe_u32 v60, v57, 16, 1
	v_lshrrev_b32_e32 v56, 16, v56
	v_add3_u32 v57, v57, v60, s65
	v_and_or_b32 v56, v57, s61, v56
	v_cvt_pk_bf16_f32 v57, v58, v59
	v_pk_mul_f32 v[58:59], v[24:25], v[174:175] op_sel_hi:[1,0]
	global_store_dwordx2 v[192:193], v[56:57], off offset:2560
	v_pk_mul_f32 v[48:49], v[48:49], v[58:59]
	v_pk_mul_f32 v[56:57], v[26:27], v[174:175] op_sel_hi:[1,0]
	s_waitcnt vmcnt(7)
	v_pk_fma_f32 v[44:45], v[52:53], v[48:49], v[44:45]
	v_pk_mul_f32 v[50:51], v[50:51], v[56:57]
	v_bfe_u32 v48, v44, 16, 1
	v_add3_u32 v44, v44, v48, s65
	v_bfe_u32 v48, v45, 16, 1
	v_pk_fma_f32 v[46:47], v[54:55], v[50:51], v[46:47]
	v_lshrrev_b32_e32 v44, 16, v44
	v_add3_u32 v45, v45, v48, s65
	v_and_or_b32 v44, v45, s61, v44
	v_cvt_pk_bf16_f32 v45, v46, v47
	v_pk_mul_f32 v[46:47], v[28:29], v[174:175] op_sel_hi:[1,0]
	global_store_dwordx2 v[192:193], v[44:45], off offset:3072
	v_pk_mul_f32 v[40:41], v[40:41], v[46:47]
	v_pk_mul_f32 v[44:45], v[30:31], v[174:175] op_sel_hi:[1,0]
	s_waitcnt vmcnt(7)
	v_pk_fma_f32 v[32:33], v[36:37], v[40:41], v[32:33]
	v_pk_mul_f32 v[42:43], v[42:43], v[44:45]
	v_pk_fma_f32 v[34:35], v[38:39], v[42:43], v[34:35]
	v_cvt_pk_bf16_f32 v32, v32, v33
	v_cvt_pk_bf16_f32 v33, v34, v35
	global_store_dwordx2 v[192:193], v[32:33], off offset:3584
	v_mov_b64_e32 v[32:33], v[146:147]
	v_mov_b64_e32 v[34:35], v[144:145]
	v_mov_b64_e32 v[36:37], v[142:143]
	v_mov_b64_e32 v[38:39], v[140:141]
	v_mov_b64_e32 v[40:41], v[138:139]
	v_mov_b64_e32 v[42:43], v[136:137]
	v_mov_b64_e32 v[44:45], v[134:135]
	v_mov_b64_e32 v[46:47], v[132:133]
	s_cbranch_scc1 .LBB0_939

.LBB0_1211:
	v_mov_b32_e32 v174, v125
	v_mov_b32_e32 v175, v121
	v_mov_b32_e32 v172, v124
	v_mov_b32_e32 v173, v120
	v_pk_mul_f32 v[174:175], v[174:175], v[174:175]
	v_mov_b32_e32 v180, v127
	v_mov_b32_e32 v181, v123
	v_pk_fma_f32 v[172:173], v[172:173], v[172:173], v[174:175]
	v_mov_b32_e32 v174, v126
	v_mov_b32_e32 v175, v122
	v_pk_mul_f32 v[180:181], v[180:181], v[180:181]
	s_mov_b32 s24, 0x17800000
	v_pk_fma_f32 v[174:175], v[174:175], v[174:175], v[180:181]
	v_pk_mul_f32 v[180:181], v[116:117], v[116:117]
	v_pk_add_f32 v[172:173], v[172:173], v[174:175]
	v_pk_mul_f32 v[174:175], v[118:119], v[118:119]
	v_pk_add_f32 v[172:173], v[172:173], v[172:173] op_sel_hi:[0,1]
	v_pk_mov_b32 v[182:183], v[180:181], v[174:175] op_sel:[1,0]
	v_mov_b32_e32 v181, v175
	v_mul_f32_e32 v172, v112, v112
	v_pk_add_f32 v[174:175], v[182:183], v[180:181]
	v_pk_fma_f32 v[180:181], v[112:113], v[112:113], v[172:173] op_sel_hi:[1,1,0]
	v_mul_f32_e32 v172, v114, v114
	v_pk_add_f32 v[174:175], v[174:175], v[174:175] op_sel_hi:[0,1]
	v_pk_fma_f32 v[182:183], v[114:115], v[114:115], v[172:173] op_sel_hi:[1,1,0]
	v_mul_f32_e32 v180, v108, v108
	v_mul_f32_e32 v182, v109, v109
	v_mul_f32_e32 v174, v110, v110
	v_mul_f32_e32 v172, v111, v111
	v_pk_add_f32 v[180:181], v[180:181], v[182:183]
	v_pk_add_f32 v[172:173], v[174:175], v[172:173]
	v_pk_mul_f32 v[174:175], v[106:107], v[106:107]
	v_pk_add_f32 v[172:173], v[180:181], v[172:173]
	v_pk_mul_f32 v[180:181], v[104:105], v[104:105]
	v_pk_add_f32 v[172:173], v[172:173], v[172:173] op_sel_hi:[0,1]
	v_pk_mov_b32 v[182:183], v[180:181], v[174:175] op_sel:[1,0]
	v_mov_b32_e32 v181, v175
	v_mul_f32_e32 v172, v100, v100
	v_pk_add_f32 v[174:175], v[182:183], v[180:181]
	v_pk_fma_f32 v[180:181], v[100:101], v[100:101], v[172:173] op_sel_hi:[1,1,0]
	v_mul_f32_e32 v172, v102, v102
	v_pk_add_f32 v[174:175], v[174:175], v[174:175] op_sel_hi:[0,1]
	v_pk_fma_f32 v[182:183], v[102:103], v[102:103], v[172:173] op_sel_hi:[1,1,0]
	v_mul_f32_e32 v180, v96, v96
	v_mul_f32_e32 v182, v97, v97
	v_mul_f32_e32 v174, v98, v98
	v_mul_f32_e32 v172, v99, v99
	v_pk_add_f32 v[180:181], v[180:181], v[182:183]
	v_pk_add_f32 v[172:173], v[174:175], v[172:173]
	s_nop 0
	v_pk_add_f32 v[172:173], v[180:181], v[172:173]
	s_nop 0
	v_add_f32_e32 v171, v172, v173
	s_waitcnt lgkmcnt(0)
	s_waitcnt lgkmcnt(0)
	s_waitcnt lgkmcnt(0)
	s_waitcnt lgkmcnt(0)
	s_waitcnt lgkmcnt(0)
	s_waitcnt lgkmcnt(0)
	s_nop 1
	v_add_f32_dpp v171, v171, v171 quad_perm:[1,0,3,2] row_mask:0xf bank_mask:0xf
	s_nop 1
	v_add_f32_dpp v171, v171, v171 quad_perm:[2,3,0,1] row_mask:0xf bank_mask:0xf
	s_nop 1
	v_add_f32_dpp v171, v171, v171 row_half_mirror row_mask:0xf bank_mask:0xf
	s_nop 1
	v_add_f32_dpp v171, v171, v171 row_mirror row_mask:0xf bank_mask:0xf
	v_mov_b32_e32 v172, v171
	s_nop 1
	v_permlane16_swap_b32_e32 v171, v172
	v_add_f32_e32 v171, v171, v172
	v_mov_b32_e32 v172, v171
	s_nop 1
	v_permlane32_swap_b32_e32 v171, v172
	v_add_f32_e32 v171, v171, v172
	v_fmamk_f32 v171, v171, 0x3a000000, v252
	v_mul_f32_e32 v172, 0x4b800000, v171
	v_cmp_gt_f32_e32 vcc, s88, v171
	s_nop 1
	v_cndmask_b32_e32 v171, v171, v172, vcc
	v_rsq_f32_e32 v171, v171
	s_nop 0
	v_mul_f32_e32 v172, 0x45800000, v171
	v_cndmask_b32_e32 v172, v171, v172, vcc
	v_pk_mul_f32 v[124:125], v[124:125], v[172:173] op_sel_hi:[1,0]
	v_pk_mul_f32 v[126:127], v[126:127], v[172:173] op_sel_hi:[1,0]
	v_pk_fma_f32 v[124:125], v[130:131], v[124:125], v[64:65]
	v_pk_fma_f32 v[126:127], v[132:133], v[126:127], v[66:67]
	v_bfe_u32 v171, v124, 16, 1
	v_add3_u32 v124, v124, v171, s65
	v_bfe_u32 v171, v125, 16, 1
	v_lshrrev_b32_e32 v124, 16, v124
	v_add3_u32 v125, v125, v171, s65
	v_and_or_b32 v124, v125, s61, v124
	s_nop 0
	s_nop 0
	s_nop 0
	v_cvt_pk_bf16_f32 v125, v126, v127
	v_add_co_u32_e32 v126, vcc, s24, v164
	v_pk_mul_f32 v[120:121], v[120:121], v[172:173] op_sel_hi:[1,0]
	s_nop 0
	v_addc_co_u32_e32 v127, vcc, 0, v165, vcc
	v_pk_fma_f32 v[120:121], v[134:135], v[120:121], v[68:69]
	global_store_dwordx2 v[126:127], v[124:125], off
	v_bfe_u32 v124, v120, 16, 1
	v_pk_mul_f32 v[122:123], v[122:123], v[172:173] op_sel_hi:[1,0]
	v_add3_u32 v120, v120, v124, s65
	v_bfe_u32 v124, v121, 16, 1
	v_pk_fma_f32 v[122:123], v[136:137], v[122:123], v[70:71]
	v_lshrrev_b32_e32 v120, 16, v120
	v_add3_u32 v121, v121, v124, s65
	v_and_or_b32 v120, v121, s61, v120
	v_bfe_u32 v121, v122, 16, 1
	v_add3_u32 v121, v122, v121, s65
	v_bfe_u32 v122, v123, 16, 1
	v_lshrrev_b32_e32 v121, 16, v121
	v_add3_u32 v122, v123, v122, s65
	v_pk_mul_f32 v[116:117], v[116:117], v[172:173] op_sel_hi:[1,0]
	v_and_or_b32 v121, v122, s61, v121
	v_pk_fma_f32 v[116:117], v[138:139], v[116:117], v[72:73]
	global_store_dwordx2 v[126:127], v[120:121], off offset:512
	v_bfe_u32 v120, v116, 16, 1
	v_pk_mul_f32 v[118:119], v[118:119], v[172:173] op_sel_hi:[1,0]
	v_add3_u32 v116, v116, v120, s65
	v_bfe_u32 v120, v117, 16, 1
	v_pk_fma_f32 v[118:119], v[140:141], v[118:119], v[74:75]
	v_lshrrev_b32_e32 v116, 16, v116
	v_add3_u32 v117, v117, v120, s65
	v_and_or_b32 v116, v117, s61, v116
	v_bfe_u32 v117, v118, 16, 1
	v_add3_u32 v117, v118, v117, s65
	v_bfe_u32 v118, v119, 16, 1
	v_lshrrev_b32_e32 v117, 16, v117
	v_add3_u32 v118, v119, v118, s65
	v_pk_mul_f32 v[112:113], v[112:113], v[172:173] op_sel_hi:[1,0]
	v_and_or_b32 v117, v118, s61, v117
	v_pk_fma_f32 v[112:113], v[142:143], v[112:113], v[76:77]
	global_store_dwordx2 v[126:127], v[116:117], off offset:1024
	v_bfe_u32 v116, v112, 16, 1
	v_pk_mul_f32 v[114:115], v[114:115], v[172:173] op_sel_hi:[1,0]
	v_add3_u32 v112, v112, v116, s65
	v_bfe_u32 v116, v113, 16, 1
	v_pk_fma_f32 v[114:115], v[144:145], v[114:115], v[78:79]
	v_lshrrev_b32_e32 v112, 16, v112
	v_add3_u32 v113, v113, v116, s65
	v_and_or_b32 v112, v113, s61, v112
	v_bfe_u32 v113, v114, 16, 1
	v_add3_u32 v113, v114, v113, s65
	v_bfe_u32 v114, v115, 16, 1
	v_lshrrev_b32_e32 v113, 16, v113
	v_add3_u32 v114, v115, v114, s65
	v_pk_mul_f32 v[108:109], v[108:109], v[172:173] op_sel_hi:[1,0]
	v_and_or_b32 v113, v114, s61, v113
	v_pk_fma_f32 v[108:109], v[146:147], v[108:109], v[80:81]
	global_store_dwordx2 v[126:127], v[112:113], off offset:1536
	v_bfe_u32 v112, v108, 16, 1
	v_pk_mul_f32 v[110:111], v[110:111], v[172:173] op_sel_hi:[1,0]
	v_add3_u32 v108, v108, v112, s65
	v_bfe_u32 v112, v109, 16, 1
	v_pk_fma_f32 v[110:111], v[148:149], v[110:111], v[82:83]
	v_lshrrev_b32_e32 v108, 16, v108
	v_add3_u32 v109, v109, v112, s65
	v_and_or_b32 v108, v109, s61, v108
	v_bfe_u32 v109, v110, 16, 1
	v_add3_u32 v109, v110, v109, s65
	v_bfe_u32 v110, v111, 16, 1
	v_lshrrev_b32_e32 v109, 16, v109
	v_add3_u32 v110, v111, v110, s65
	v_pk_mul_f32 v[104:105], v[104:105], v[172:173] op_sel_hi:[1,0]
	v_and_or_b32 v109, v110, s61, v109
	v_pk_fma_f32 v[104:105], v[150:151], v[104:105], v[84:85]
	global_store_dwordx2 v[126:127], v[108:109], off offset:2048
	v_bfe_u32 v108, v104, 16, 1
	v_pk_mul_f32 v[106:107], v[106:107], v[172:173] op_sel_hi:[1,0]
	v_add3_u32 v104, v104, v108, s65
	v_bfe_u32 v108, v105, 16, 1
	v_pk_fma_f32 v[106:107], v[152:153], v[106:107], v[86:87]
	v_lshrrev_b32_e32 v104, 16, v104
	v_add3_u32 v105, v105, v108, s65
	v_and_or_b32 v104, v105, s61, v104
	v_bfe_u32 v105, v106, 16, 1
	v_add3_u32 v105, v106, v105, s65
	v_bfe_u32 v106, v107, 16, 1
	v_lshrrev_b32_e32 v105, 16, v105
	v_add3_u32 v106, v107, v106, s65
	v_pk_mul_f32 v[100:101], v[100:101], v[172:173] op_sel_hi:[1,0]
	v_and_or_b32 v105, v106, s61, v105
	v_pk_fma_f32 v[100:101], v[154:155], v[100:101], v[88:89]
	global_store_dwordx2 v[126:127], v[104:105], off offset:2560
	v_bfe_u32 v104, v100, 16, 1
	v_pk_mul_f32 v[102:103], v[102:103], v[172:173] op_sel_hi:[1,0]
	v_add3_u32 v100, v100, v104, s65
	v_bfe_u32 v104, v101, 16, 1
	v_pk_fma_f32 v[102:103], v[156:157], v[102:103], v[90:91]
	v_lshrrev_b32_e32 v100, 16, v100
	v_add3_u32 v101, v101, v104, s65
	v_and_or_b32 v100, v101, s61, v100
	v_bfe_u32 v101, v102, 16, 1
	v_add3_u32 v101, v102, v101, s65
	v_bfe_u32 v102, v103, 16, 1
	v_lshrrev_b32_e32 v101, 16, v101
	v_add3_u32 v102, v103, v102, s65
	v_pk_mul_f32 v[96:97], v[96:97], v[172:173] op_sel_hi:[1,0]
	v_and_or_b32 v101, v102, s61, v101
	v_pk_fma_f32 v[96:97], v[158:159], v[96:97], v[92:93]
	global_store_dwordx2 v[126:127], v[100:101], off offset:3072
	v_bfe_u32 v100, v96, 16, 1
	v_pk_mul_f32 v[98:99], v[98:99], v[172:173] op_sel_hi:[1,0]
	v_add3_u32 v96, v96, v100, s65
	v_bfe_u32 v100, v97, 16, 1
	v_pk_fma_f32 v[98:99], v[160:161], v[98:99], v[94:95]
	v_lshrrev_b32_e32 v96, 16, v96
	v_add3_u32 v97, v97, v100, s65
	v_and_or_b32 v96, v97, s61, v96
	v_bfe_u32 v97, v98, 16, 1
	v_add3_u32 v97, v98, v97, s65
	v_bfe_u32 v98, v99, 16, 1
	v_lshrrev_b32_e32 v97, 16, v97
	v_add3_u32 v98, v99, v98, s65
	v_and_or_b32 v97, v98, s61, v97
	global_store_dwordx2 v[126:127], v[96:97], off offset:3584
	s_branch .LBB0_1205

.LBB0_1222:
	v_mad_i64_i32 v[32:33], s[10:11], s12, v224, v[102:103]
	v_mad_i64_i32 v[34:35], s[10:11], s12, v224, v[104:105]
	s_movk_i32 s10, 0x1000
	global_load_dwordx4 v[116:119], v[82:83], off
	global_load_dwordx4 v[120:123], v[82:83], off offset:1024
	global_load_dwordx4 v[124:127], v[32:33], off
	global_load_dwordx4 v[128:131], v[32:33], off offset:1024
	global_load_dwordx4 v[132:135], v[34:35], off
	global_load_dwordx4 v[136:139], v[34:35], off offset:1024
	global_load_dwordx4 v[140:143], v[82:83], off offset:2048
	global_load_dwordx4 v[144:147], v[82:83], off offset:3072
	global_load_dwordx4 v[148:151], v[32:33], off offset:2048
	global_load_dwordx4 v[152:155], v[32:33], off offset:3072
	global_load_dwordx4 v[156:159], v[34:35], off offset:2048
	global_load_dwordx4 v[160:163], v[34:35], off offset:3072
	v_add_co_u32_e32 v32, vcc, s10, v32
	s_nop 1
	v_addc_co_u32_e32 v33, vcc, 0, v33, vcc
	v_add_co_u32_e32 v34, vcc, s10, v34
	s_nop 1
	v_addc_co_u32_e32 v35, vcc, 0, v35, vcc
	global_load_dwordx4 v[72:75], v[92:93], off
	global_load_dwordx4 v[64:67], v[94:95], off
	global_load_dwordx4 v[76:79], v[32:33], off
	global_load_dwordx4 v[60:63], v[32:33], off offset:1024
	global_load_dwordx4 v[68:71], v[34:35], off
	global_load_dwordx4 v[56:59], v[34:35], off offset:1024
	global_load_dwordx4 v[48:51], v[96:97], off
	global_load_dwordx4 v[40:43], v[98:99], off
	global_load_dwordx4 v[52:55], v[32:33], off offset:2048
	global_load_dwordx4 v[36:39], v[32:33], off offset:3072
	global_load_dwordx4 v[44:47], v[34:35], off offset:2048
	s_nop 0
	global_load_dwordx4 v[32:35], v[34:35], off offset:3072
	v_mov_b32_e32 v166, v29
	v_mov_b32_e32 v167, v25
	v_mov_b32_e32 v164, v28
	v_mov_b32_e32 v165, v24
	v_pk_mul_f32 v[166:167], v[166:167], v[166:167]
	v_mov_b32_e32 v168, v31
	v_mov_b32_e32 v169, v27
	v_pk_fma_f32 v[164:165], v[164:165], v[164:165], v[166:167]
	v_mov_b32_e32 v166, v30
	v_mov_b32_e32 v167, v26
	v_pk_mul_f32 v[168:169], v[168:169], v[168:169]
	s_mov_b32 s10, 0x17800000
	v_pk_fma_f32 v[166:167], v[166:167], v[166:167], v[168:169]
	v_pk_mul_f32 v[168:169], v[20:21], v[20:21]
	v_pk_add_f32 v[164:165], v[164:165], v[166:167]
	v_pk_mul_f32 v[166:167], v[22:23], v[22:23]
	v_pk_add_f32 v[164:165], v[164:165], v[164:165] op_sel_hi:[0,1]
	v_pk_mov_b32 v[170:171], v[168:169], v[166:167] op_sel:[1,0]
	v_mov_b32_e32 v169, v167
	v_mul_f32_e32 v164, v16, v16
	v_pk_add_f32 v[166:167], v[170:171], v[168:169]
	v_pk_fma_f32 v[168:169], v[16:17], v[16:17], v[164:165] op_sel_hi:[1,1,0]
	v_mul_f32_e32 v164, v18, v18
	v_pk_add_f32 v[166:167], v[166:167], v[166:167] op_sel_hi:[0,1]
	v_pk_fma_f32 v[170:171], v[18:19], v[18:19], v[164:165] op_sel_hi:[1,1,0]
	v_mul_f32_e32 v168, v12, v12
	v_mul_f32_e32 v170, v13, v13
	v_mul_f32_e32 v166, v14, v14
	v_mul_f32_e32 v164, v15, v15
	v_pk_add_f32 v[168:169], v[168:169], v[170:171]
	v_pk_add_f32 v[164:165], v[166:167], v[164:165]
	v_pk_mul_f32 v[166:167], v[10:11], v[10:11]
	v_pk_add_f32 v[164:165], v[168:169], v[164:165]
	v_pk_mul_f32 v[168:169], v[8:9], v[8:9]
	v_pk_add_f32 v[164:165], v[164:165], v[164:165] op_sel_hi:[0,1]
	v_pk_mov_b32 v[170:171], v[168:169], v[166:167] op_sel:[1,0]
	v_mov_b32_e32 v169, v167
	v_mul_f32_e32 v164, v4, v4
	v_pk_add_f32 v[166:167], v[170:171], v[168:169]
	v_pk_fma_f32 v[168:169], v[4:5], v[4:5], v[164:165] op_sel_hi:[1,1,0]
	v_mul_f32_e32 v164, v6, v6
	v_pk_add_f32 v[166:167], v[166:167], v[166:167] op_sel_hi:[0,1]
	v_pk_fma_f32 v[170:171], v[6:7], v[6:7], v[164:165] op_sel_hi:[1,1,0]
	v_mul_f32_e32 v168, v0, v0
	v_mul_f32_e32 v170, v1, v1
	v_mul_f32_e32 v166, v2, v2
	v_mul_f32_e32 v164, v3, v3
	v_pk_add_f32 v[168:169], v[168:169], v[170:171]
	v_pk_add_f32 v[164:165], v[166:167], v[164:165]
	s_nop 0
	v_pk_add_f32 v[164:165], v[168:169], v[164:165]
	s_nop 0
	v_add_f32_e32 v164, v164, v165
	s_waitcnt lgkmcnt(0)
	s_waitcnt lgkmcnt(0)
	s_waitcnt lgkmcnt(0)
	s_waitcnt lgkmcnt(0)
	s_waitcnt lgkmcnt(0)
	s_waitcnt lgkmcnt(0)
	s_nop 1
	v_add_f32_dpp v164, v164, v164 quad_perm:[1,0,3,2] row_mask:0xf bank_mask:0xf
	s_nop 1
	v_add_f32_dpp v164, v164, v164 quad_perm:[2,3,0,1] row_mask:0xf bank_mask:0xf
	s_nop 1
	v_add_f32_dpp v164, v164, v164 row_half_mirror row_mask:0xf bank_mask:0xf
	s_nop 1
	v_add_f32_dpp v164, v164, v164 row_mirror row_mask:0xf bank_mask:0xf
	v_mov_b32_e32 v165, v164
	s_nop 1
	v_permlane16_swap_b32_e32 v164, v165
	v_add_f32_e32 v164, v164, v165
	v_mov_b32_e32 v165, v164
	s_nop 1
	v_permlane32_swap_b32_e32 v164, v165
	v_add_f32_e32 v164, v164, v165
	v_fmamk_f32 v164, v164, 0x3a000000, v252
	v_mul_f32_e32 v165, 0x4b800000, v164
	v_cmp_gt_f32_e32 vcc, s88, v164
	s_nop 1
	v_cndmask_b32_e32 v164, v164, v165, vcc
	v_rsq_f32_e32 v164, v164
	s_nop 0
	v_mul_f32_e32 v165, 0x45800000, v164
	v_cndmask_b32_e32 v164, v164, v165, vcc
	v_pk_mul_f32 v[30:31], v[30:31], v[164:165] op_sel_hi:[1,0]
	v_pk_mul_f32 v[28:29], v[28:29], v[164:165] op_sel_hi:[1,0]
	s_waitcnt vmcnt(23)
	v_pk_mul_f32 v[30:31], v[118:119], v[30:31]
	v_pk_mul_f32 v[28:29], v[116:117], v[28:29]
	s_waitcnt vmcnt(21)
	v_pk_add_f32 v[118:119], v[124:125], 1.0 op_sel_hi:[1,0]
	v_pk_add_f32 v[116:117], v[126:127], 1.0 op_sel_hi:[1,0]
	s_waitcnt vmcnt(19)
	v_pk_fma_f32 v[28:29], v[118:119], v[28:29], v[132:133]
	v_pk_fma_f32 v[30:31], v[116:117], v[30:31], v[134:135]
	v_bfe_u32 v116, v28, 16, 1
	v_add3_u32 v28, v28, v116, s65
	v_bfe_u32 v116, v29, 16, 1
	v_lshrrev_b32_e32 v28, 16, v28
	v_add3_u32 v29, v29, v116, s65
	v_and_or_b32 v28, v29, s61, v28
	s_nop 0
	s_nop 0
	s_nop 0
	v_cvt_pk_bf16_f32 v29, v30, v31
	v_add_co_u32_e32 v30, vcc, s10, v108
	v_pk_mul_f32 v[24:25], v[24:25], v[164:165] op_sel_hi:[1,0]
	s_nop 0
	v_addc_co_u32_e32 v31, vcc, 0, v109, vcc
	v_pk_mul_f32 v[26:27], v[26:27], v[164:165] op_sel_hi:[1,0]
	v_pk_mul_f32 v[24:25], v[120:121], v[24:25]
	v_pk_add_f32 v[108:109], v[128:129], 1.0 op_sel_hi:[1,0]
	global_store_dwordx2 v[30:31], v[28:29], off
	v_pk_mul_f32 v[26:27], v[122:123], v[26:27]
	v_pk_add_f32 v[28:29], v[130:131], 1.0 op_sel_hi:[1,0]
	s_waitcnt vmcnt(19)
	v_pk_fma_f32 v[24:25], v[108:109], v[24:25], v[136:137]
	v_pk_fma_f32 v[26:27], v[28:29], v[26:27], v[138:139]
	v_bfe_u32 v28, v24, 16, 1
	v_add3_u32 v24, v24, v28, s65
	v_bfe_u32 v28, v25, 16, 1
	v_lshrrev_b32_e32 v24, 16, v24
	v_add3_u32 v25, v25, v28, s65
	v_and_or_b32 v24, v25, s61, v24
	v_pk_mul_f32 v[20:21], v[20:21], v[164:165] op_sel_hi:[1,0]
	v_cvt_pk_bf16_f32 v25, v26, v27
	v_pk_mul_f32 v[22:23], v[22:23], v[164:165] op_sel_hi:[1,0]
	s_waitcnt vmcnt(18)
	v_pk_mul_f32 v[20:21], v[140:141], v[20:21]
	s_waitcnt vmcnt(16)
	v_pk_add_f32 v[26:27], v[148:149], 1.0 op_sel_hi:[1,0]
	global_store_dwordx2 v[30:31], v[24:25], off offset:512
	v_pk_mul_f32 v[22:23], v[142:143], v[22:23]
	v_pk_add_f32 v[24:25], v[150:151], 1.0 op_sel_hi:[1,0]
	s_waitcnt vmcnt(15)
	v_pk_fma_f32 v[20:21], v[26:27], v[20:21], v[156:157]
	v_pk_fma_f32 v[22:23], v[24:25], v[22:23], v[158:159]
	v_bfe_u32 v24, v20, 16, 1
	v_add3_u32 v20, v20, v24, s65
	v_bfe_u32 v24, v21, 16, 1
	v_lshrrev_b32_e32 v20, 16, v20
	v_add3_u32 v21, v21, v24, s65
	v_and_or_b32 v20, v21, s61, v20
	v_pk_mul_f32 v[16:17], v[16:17], v[164:165] op_sel_hi:[1,0]
	v_cvt_pk_bf16_f32 v21, v22, v23
	v_pk_mul_f32 v[18:19], v[18:19], v[164:165] op_sel_hi:[1,0]
	v_pk_mul_f32 v[16:17], v[144:145], v[16:17]
	v_pk_add_f32 v[22:23], v[152:153], 1.0 op_sel_hi:[1,0]
	global_store_dwordx2 v[30:31], v[20:21], off offset:1024
	v_pk_mul_f32 v[18:19], v[146:147], v[18:19]
	v_pk_add_f32 v[20:21], v[154:155], 1.0 op_sel_hi:[1,0]
	s_waitcnt vmcnt(15)
	v_pk_fma_f32 v[16:17], v[22:23], v[16:17], v[160:161]
	v_pk_fma_f32 v[18:19], v[20:21], v[18:19], v[162:163]
	v_bfe_u32 v20, v16, 16, 1
	v_add3_u32 v16, v16, v20, s65
	v_bfe_u32 v20, v17, 16, 1
	v_lshrrev_b32_e32 v16, 16, v16
	v_add3_u32 v17, v17, v20, s65
	v_and_or_b32 v16, v17, s61, v16
	v_pk_mul_f32 v[12:13], v[12:13], v[164:165] op_sel_hi:[1,0]
	v_cvt_pk_bf16_f32 v17, v18, v19
	v_pk_mul_f32 v[14:15], v[14:15], v[164:165] op_sel_hi:[1,0]
	s_waitcnt vmcnt(14)
	v_pk_mul_f32 v[12:13], v[72:73], v[12:13]
	s_waitcnt vmcnt(12)
	v_pk_add_f32 v[18:19], v[76:77], 1.0 op_sel_hi:[1,0]
	global_store_dwordx2 v[30:31], v[16:17], off offset:1536
	v_pk_mul_f32 v[14:15], v[74:75], v[14:15]
	v_pk_add_f32 v[16:17], v[78:79], 1.0 op_sel_hi:[1,0]
	s_waitcnt vmcnt(11)
	v_pk_fma_f32 v[12:13], v[18:19], v[12:13], v[68:69]
	v_pk_fma_f32 v[14:15], v[16:17], v[14:15], v[70:71]
	v_bfe_u32 v16, v12, 16, 1
	v_add3_u32 v12, v12, v16, s65
	v_bfe_u32 v16, v13, 16, 1
	v_lshrrev_b32_e32 v12, 16, v12
	v_add3_u32 v13, v13, v16, s65
	v_and_or_b32 v12, v13, s61, v12
	v_pk_mul_f32 v[8:9], v[8:9], v[164:165] op_sel_hi:[1,0]
	v_cvt_pk_bf16_f32 v13, v14, v15
	v_pk_mul_f32 v[10:11], v[10:11], v[164:165] op_sel_hi:[1,0]
	v_pk_mul_f32 v[8:9], v[64:65], v[8:9]
	v_pk_add_f32 v[14:15], v[60:61], 1.0 op_sel_hi:[1,0]
	global_store_dwordx2 v[30:31], v[12:13], off offset:2048
	v_pk_mul_f32 v[10:11], v[66:67], v[10:11]
	v_pk_add_f32 v[12:13], v[62:63], 1.0 op_sel_hi:[1,0]
	s_waitcnt vmcnt(11)
	v_pk_fma_f32 v[8:9], v[14:15], v[8:9], v[56:57]
	v_pk_fma_f32 v[10:11], v[12:13], v[10:11], v[58:59]
	v_bfe_u32 v12, v8, 16, 1
	v_add3_u32 v8, v8, v12, s65
	v_bfe_u32 v12, v9, 16, 1
	v_lshrrev_b32_e32 v8, 16, v8
	v_add3_u32 v9, v9, v12, s65
	v_and_or_b32 v8, v9, s61, v8
	v_pk_mul_f32 v[4:5], v[4:5], v[164:165] op_sel_hi:[1,0]
	v_cvt_pk_bf16_f32 v9, v10, v11
	v_pk_mul_f32 v[6:7], v[6:7], v[164:165] op_sel_hi:[1,0]
	s_waitcnt vmcnt(10)
	v_pk_mul_f32 v[4:5], v[48:49], v[4:5]
	s_waitcnt vmcnt(8)
	v_pk_add_f32 v[10:11], v[52:53], 1.0 op_sel_hi:[1,0]
	global_store_dwordx2 v[30:31], v[8:9], off offset:2560
	v_pk_mul_f32 v[6:7], v[50:51], v[6:7]
	v_pk_add_f32 v[8:9], v[54:55], 1.0 op_sel_hi:[1,0]
	s_waitcnt vmcnt(7)
	v_pk_fma_f32 v[4:5], v[10:11], v[4:5], v[44:45]
	v_pk_fma_f32 v[6:7], v[8:9], v[6:7], v[46:47]
	v_bfe_u32 v8, v4, 16, 1
	v_add3_u32 v4, v4, v8, s65
	v_bfe_u32 v8, v5, 16, 1
	v_lshrrev_b32_e32 v4, 16, v4
	v_add3_u32 v5, v5, v8, s65
	v_and_or_b32 v4, v5, s61, v4
	v_pk_mul_f32 v[0:1], v[0:1], v[164:165] op_sel_hi:[1,0]
	v_cvt_pk_bf16_f32 v5, v6, v7
	v_pk_mul_f32 v[2:3], v[2:3], v[164:165] op_sel_hi:[1,0]
	v_pk_mul_f32 v[0:1], v[40:41], v[0:1]
	v_pk_add_f32 v[6:7], v[36:37], 1.0 op_sel_hi:[1,0]
	global_store_dwordx2 v[30:31], v[4:5], off offset:3072
	v_pk_mul_f32 v[2:3], v[42:43], v[2:3]
	v_pk_add_f32 v[4:5], v[38:39], 1.0 op_sel_hi:[1,0]
	s_waitcnt vmcnt(7)
	v_pk_fma_f32 v[0:1], v[6:7], v[0:1], v[32:33]
	v_pk_fma_f32 v[2:3], v[4:5], v[2:3], v[34:35]
	v_bfe_u32 v4, v0, 16, 1
	v_add3_u32 v0, v0, v4, s65
	v_bfe_u32 v4, v1, 16, 1
	v_lshrrev_b32_e32 v0, 16, v0
	v_add3_u32 v1, v1, v4, s65
	v_and_or_b32 v0, v1, s61, v0
	v_bfe_u32 v1, v2, 16, 1
	v_add3_u32 v1, v2, v1, s65
	v_bfe_u32 v2, v3, 16, 1
	v_lshrrev_b32_e32 v1, 16, v1
	v_add3_u32 v2, v3, v2, s65
	v_and_or_b32 v1, v2, s61, v1
	global_store_dwordx2 v[30:31], v[0:1], off offset:3584
	s_branch .LBB0_1216
